# batched the 60 serialized wave reductions of the adaLN GEMV (15 independent sums per ds_bpermute round trip) + final output stores rewritten as full 128-byte-line stores via DPP lane-pair exchange
# speedup vs baseline: 1.1241x; 1.0098x over previous
.LBB0_9:
	global_load_dword v66, v[30:31], off
	global_load_dword v67, v[30:31], off offset:2048
	s_ashr_i32 s11, s10, 31
	s_lshl_b64 s[12:13], s[10:11], 2
	s_add_u32 s12, s64, s12
	s_addc_u32 s13, s65, s13
	v_lshl_add_u64 v[62:63], s[12:13], 0, v[26:27]
	v_lshl_add_u64 v[64:65], s[12:13], 0, v[28:29]
	global_load_dwordx4 v[18:21], v[62:63], off
	global_load_dwordx4 v[22:25], v[64:65], off
	global_load_dword v58, v[34:35], off
	global_load_dword v56, v[36:37], off
	global_load_dword v60, v[32:33], off
	global_load_dword v61, v[40:41], off
	global_load_dword v59, v[42:43], off
	global_load_dword v57, v[44:45], off
	global_load_dword v55, v[38:39], off
	global_load_dword v54, v[38:39], off offset:2048
	global_load_dwordx4 v[10:13], v[62:63], off offset:16
	global_load_dwordx4 v[2:5], v[62:63], off offset:32
	global_load_dwordx4 v[6:9], v[64:65], off offset:32
	global_load_dwordx4 v[14:17], v[64:65], off offset:16
	s_waitcnt vmcnt(15)
	v_mul_f32_e32 v62, 0xbfb8aa3b, v66
	s_waitcnt vmcnt(14)
	v_mul_f32_e32 v63, 0xbfb8aa3b, v67
	v_exp_f32_e32 v62, v62
	v_exp_f32_e32 v63, v63
	v_add_f32_e32 v62, 1.0, v62
	v_add_f32_e32 v63, 1.0, v63
	v_rcp_f32_e32 v62, v62
	v_rcp_f32_e32 v64, v63
	v_mul_f32_e32 v63, v66, v62
	v_mul_f32_e32 v62, v67, v64
	s_waitcnt vmcnt(13)
	v_fma_f32 v68, v63, v18, 0
	s_waitcnt vmcnt(12)
	v_fmac_f32_e32 v68, v62, v22
	v_fma_f32 v69, v63, v19, 0
	v_fmac_f32_e32 v69, v62, v23
	v_fma_f32 v70, v63, v20, 0
	v_fmac_f32_e32 v70, v62, v24
	v_fma_f32 v71, v63, v21, 0
	v_fmac_f32_e32 v71, v62, v25
	s_waitcnt vmcnt(3)
	v_fma_f32 v72, v63, v10, 0
	s_waitcnt vmcnt(0)
	v_fmac_f32_e32 v72, v62, v14
	v_fma_f32 v73, v63, v11, 0
	v_fmac_f32_e32 v73, v62, v15
	v_fma_f32 v74, v63, v12, 0
	v_fmac_f32_e32 v74, v62, v16
	v_fma_f32 v75, v63, v13, 0
	v_fmac_f32_e32 v75, v62, v17
	v_fma_f32 v76, v63, v2, 0
	v_fmac_f32_e32 v76, v62, v6
	v_fma_f32 v77, v63, v3, 0
	v_fmac_f32_e32 v77, v62, v7
	v_fma_f32 v78, v63, v4, 0
	v_fmac_f32_e32 v78, v62, v8
	v_fma_f32 v79, v63, v5, 0
	v_fmac_f32_e32 v79, v62, v9
	v_mul_f32_e32 v62, 0xbfb8aa3b, v60
	v_exp_f32_e32 v62, v62
	s_waitcnt lgkmcnt(0)
	v_mul_f32_e32 v63, 0xbfb8aa3b, v61
	v_exp_f32_e32 v63, v63
	v_add_f32_e32 v62, 1.0, v62
	v_rcp_f32_e32 v62, v62
	v_add_f32_e32 v63, 1.0, v63
	v_rcp_f32_e32 v63, v63
	v_mul_f32_e32 v60, v60, v62
	v_fma_f32 v80, v18, v60, 0
	v_mul_f32_e32 v61, v61, v63
	v_fmac_f32_e32 v80, v22, v61
	v_fma_f32 v81, v19, v60, 0
	v_fmac_f32_e32 v81, v23, v61
	v_fma_f32 v82, v20, v60, 0
	v_fmac_f32_e32 v82, v24, v61
	ds_bpermute_b32 v83, v1, v68
	ds_bpermute_b32 v84, v1, v69
	ds_bpermute_b32 v85, v1, v70
	ds_bpermute_b32 v86, v1, v71
	ds_bpermute_b32 v87, v1, v72
	ds_bpermute_b32 v88, v1, v73
	ds_bpermute_b32 v89, v1, v74
	ds_bpermute_b32 v90, v1, v75
	ds_bpermute_b32 v91, v1, v76
	ds_bpermute_b32 v92, v1, v77
	ds_bpermute_b32 v93, v1, v78
	ds_bpermute_b32 v94, v1, v79
	ds_bpermute_b32 v95, v1, v80
	ds_bpermute_b32 v96, v1, v81
	ds_bpermute_b32 v97, v1, v82
	s_waitcnt lgkmcnt(14)
	v_add_f32_e32 v68, v68, v83
	s_waitcnt lgkmcnt(13)
	v_add_f32_e32 v69, v69, v84
	s_waitcnt lgkmcnt(12)
	v_add_f32_e32 v70, v70, v85
	s_waitcnt lgkmcnt(11)
	v_add_f32_e32 v71, v71, v86
	s_waitcnt lgkmcnt(10)
	v_add_f32_e32 v72, v72, v87
	s_waitcnt lgkmcnt(9)
	v_add_f32_e32 v73, v73, v88
	s_waitcnt lgkmcnt(8)
	v_add_f32_e32 v74, v74, v89
	s_waitcnt lgkmcnt(7)
	v_add_f32_e32 v75, v75, v90
	s_waitcnt lgkmcnt(6)
	v_add_f32_e32 v76, v76, v91
	s_waitcnt lgkmcnt(5)
	v_add_f32_e32 v77, v77, v92
	s_waitcnt lgkmcnt(4)
	v_add_f32_e32 v78, v78, v93
	s_waitcnt lgkmcnt(3)
	v_add_f32_e32 v79, v79, v94
	s_waitcnt lgkmcnt(2)
	v_add_f32_e32 v80, v80, v95
	s_waitcnt lgkmcnt(1)
	v_add_f32_e32 v81, v81, v96
	s_waitcnt lgkmcnt(0)
	v_add_f32_e32 v82, v82, v97
	ds_bpermute_b32 v83, v46, v68
	ds_bpermute_b32 v84, v46, v69
	ds_bpermute_b32 v85, v46, v70
	ds_bpermute_b32 v86, v46, v71
	ds_bpermute_b32 v87, v46, v72
	ds_bpermute_b32 v88, v46, v73
	ds_bpermute_b32 v89, v46, v74
	ds_bpermute_b32 v90, v46, v75
	ds_bpermute_b32 v91, v46, v76
	ds_bpermute_b32 v92, v46, v77
	ds_bpermute_b32 v93, v46, v78
	ds_bpermute_b32 v94, v46, v79
	ds_bpermute_b32 v95, v46, v80
	ds_bpermute_b32 v96, v46, v81
	ds_bpermute_b32 v97, v46, v82
	s_waitcnt lgkmcnt(14)
	v_add_f32_e32 v68, v68, v83
	s_waitcnt lgkmcnt(13)
	v_add_f32_e32 v69, v69, v84
	s_waitcnt lgkmcnt(12)
	v_add_f32_e32 v70, v70, v85
	s_waitcnt lgkmcnt(11)
	v_add_f32_e32 v71, v71, v86
	s_waitcnt lgkmcnt(10)
	v_add_f32_e32 v72, v72, v87
	s_waitcnt lgkmcnt(9)
	v_add_f32_e32 v73, v73, v88
	s_waitcnt lgkmcnt(8)
	v_add_f32_e32 v74, v74, v89
	s_waitcnt lgkmcnt(7)
	v_add_f32_e32 v75, v75, v90
	s_waitcnt lgkmcnt(6)
	v_add_f32_e32 v76, v76, v91
	s_waitcnt lgkmcnt(5)
	v_add_f32_e32 v77, v77, v92
	s_waitcnt lgkmcnt(4)
	v_add_f32_e32 v78, v78, v93
	s_waitcnt lgkmcnt(3)
	v_add_f32_e32 v79, v79, v94
	s_waitcnt lgkmcnt(2)
	v_add_f32_e32 v80, v80, v95
	s_waitcnt lgkmcnt(1)
	v_add_f32_e32 v81, v81, v96
	s_waitcnt lgkmcnt(0)
	v_add_f32_e32 v82, v82, v97
	ds_bpermute_b32 v83, v47, v68
	ds_bpermute_b32 v84, v47, v69
	ds_bpermute_b32 v85, v47, v70
	ds_bpermute_b32 v86, v47, v71
	ds_bpermute_b32 v87, v47, v72
	ds_bpermute_b32 v88, v47, v73
	ds_bpermute_b32 v89, v47, v74
	ds_bpermute_b32 v90, v47, v75
	ds_bpermute_b32 v91, v47, v76
	ds_bpermute_b32 v92, v47, v77
	ds_bpermute_b32 v93, v47, v78
	ds_bpermute_b32 v94, v47, v79
	ds_bpermute_b32 v95, v47, v80
	ds_bpermute_b32 v96, v47, v81
	ds_bpermute_b32 v97, v47, v82
	s_waitcnt lgkmcnt(14)
	v_add_f32_e32 v68, v68, v83
	s_waitcnt lgkmcnt(13)
	v_add_f32_e32 v69, v69, v84
	s_waitcnt lgkmcnt(12)
	v_add_f32_e32 v70, v70, v85
	s_waitcnt lgkmcnt(11)
	v_add_f32_e32 v71, v71, v86
	s_waitcnt lgkmcnt(10)
	v_add_f32_e32 v72, v72, v87
	s_waitcnt lgkmcnt(9)
	v_add_f32_e32 v73, v73, v88
	s_waitcnt lgkmcnt(8)
	v_add_f32_e32 v74, v74, v89
	s_waitcnt lgkmcnt(7)
	v_add_f32_e32 v75, v75, v90
	s_waitcnt lgkmcnt(6)
	v_add_f32_e32 v76, v76, v91
	s_waitcnt lgkmcnt(5)
	v_add_f32_e32 v77, v77, v92
	s_waitcnt lgkmcnt(4)
	v_add_f32_e32 v78, v78, v93
	s_waitcnt lgkmcnt(3)
	v_add_f32_e32 v79, v79, v94
	s_waitcnt lgkmcnt(2)
	v_add_f32_e32 v80, v80, v95
	s_waitcnt lgkmcnt(1)
	v_add_f32_e32 v81, v81, v96
	s_waitcnt lgkmcnt(0)
	v_add_f32_e32 v82, v82, v97
	ds_bpermute_b32 v83, v48, v68
	ds_bpermute_b32 v84, v48, v69
	ds_bpermute_b32 v85, v48, v70
	ds_bpermute_b32 v86, v48, v71
	ds_bpermute_b32 v87, v48, v72
	ds_bpermute_b32 v88, v48, v73
	ds_bpermute_b32 v89, v48, v74
	ds_bpermute_b32 v90, v48, v75
	ds_bpermute_b32 v91, v48, v76
	ds_bpermute_b32 v92, v48, v77
	ds_bpermute_b32 v93, v48, v78
	ds_bpermute_b32 v94, v48, v79
	ds_bpermute_b32 v95, v48, v80
	ds_bpermute_b32 v96, v48, v81
	ds_bpermute_b32 v97, v48, v82
	s_waitcnt lgkmcnt(14)
	v_add_f32_e32 v68, v68, v83
	s_waitcnt lgkmcnt(13)
	v_add_f32_e32 v69, v69, v84
	s_waitcnt lgkmcnt(12)
	v_add_f32_e32 v70, v70, v85
	s_waitcnt lgkmcnt(11)
	v_add_f32_e32 v71, v71, v86
	s_waitcnt lgkmcnt(10)
	v_add_f32_e32 v72, v72, v87
	s_waitcnt lgkmcnt(9)
	v_add_f32_e32 v73, v73, v88
	s_waitcnt lgkmcnt(8)
	v_add_f32_e32 v74, v74, v89
	s_waitcnt lgkmcnt(7)
	v_add_f32_e32 v75, v75, v90
	s_waitcnt lgkmcnt(6)
	v_add_f32_e32 v76, v76, v91
	s_waitcnt lgkmcnt(5)
	v_add_f32_e32 v77, v77, v92
	s_waitcnt lgkmcnt(4)
	v_add_f32_e32 v78, v78, v93
	s_waitcnt lgkmcnt(3)
	v_add_f32_e32 v79, v79, v94
	s_waitcnt lgkmcnt(2)
	v_add_f32_e32 v80, v80, v95
	s_waitcnt lgkmcnt(1)
	v_add_f32_e32 v81, v81, v96
	s_waitcnt lgkmcnt(0)
	v_add_f32_e32 v82, v82, v97
	ds_bpermute_b32 v83, v49, v68
	ds_bpermute_b32 v84, v49, v69
	ds_bpermute_b32 v85, v49, v70
	ds_bpermute_b32 v86, v49, v71
	ds_bpermute_b32 v87, v49, v72
	ds_bpermute_b32 v88, v49, v73
	ds_bpermute_b32 v89, v49, v74
	ds_bpermute_b32 v90, v49, v75
	ds_bpermute_b32 v91, v49, v76
	ds_bpermute_b32 v92, v49, v77
	ds_bpermute_b32 v93, v49, v78
	ds_bpermute_b32 v94, v49, v79
	ds_bpermute_b32 v95, v49, v80
	ds_bpermute_b32 v96, v49, v81
	ds_bpermute_b32 v97, v49, v82
	s_waitcnt lgkmcnt(14)
	v_add_f32_e32 v68, v68, v83
	s_waitcnt lgkmcnt(13)
	v_add_f32_e32 v69, v69, v84
	s_waitcnt lgkmcnt(12)
	v_add_f32_e32 v70, v70, v85
	s_waitcnt lgkmcnt(11)
	v_add_f32_e32 v71, v71, v86
	s_waitcnt lgkmcnt(10)
	v_add_f32_e32 v72, v72, v87
	s_waitcnt lgkmcnt(9)
	v_add_f32_e32 v73, v73, v88
	s_waitcnt lgkmcnt(8)
	v_add_f32_e32 v74, v74, v89
	s_waitcnt lgkmcnt(7)
	v_add_f32_e32 v75, v75, v90
	s_waitcnt lgkmcnt(6)
	v_add_f32_e32 v76, v76, v91
	s_waitcnt lgkmcnt(5)
	v_add_f32_e32 v77, v77, v92
	s_waitcnt lgkmcnt(4)
	v_add_f32_e32 v78, v78, v93
	s_waitcnt lgkmcnt(3)
	v_add_f32_e32 v79, v79, v94
	s_waitcnt lgkmcnt(2)
	v_add_f32_e32 v80, v80, v95
	s_waitcnt lgkmcnt(1)
	v_add_f32_e32 v81, v81, v96
	s_waitcnt lgkmcnt(0)
	v_add_f32_e32 v82, v82, v97
	ds_bpermute_b32 v83, v50, v68
	ds_bpermute_b32 v84, v50, v69
	ds_bpermute_b32 v85, v50, v70
	ds_bpermute_b32 v86, v50, v71
	ds_bpermute_b32 v87, v50, v72
	ds_bpermute_b32 v88, v50, v73
	ds_bpermute_b32 v89, v50, v74
	ds_bpermute_b32 v90, v50, v75
	ds_bpermute_b32 v91, v50, v76
	ds_bpermute_b32 v92, v50, v77
	ds_bpermute_b32 v93, v50, v78
	ds_bpermute_b32 v94, v50, v79
	ds_bpermute_b32 v95, v50, v80
	ds_bpermute_b32 v96, v50, v81
	ds_bpermute_b32 v97, v50, v82
	s_waitcnt lgkmcnt(14)
	v_add_f32_e32 v68, v68, v83
	s_waitcnt lgkmcnt(13)
	v_add_f32_e32 v69, v69, v84
	s_waitcnt lgkmcnt(12)
	v_add_f32_e32 v70, v70, v85
	s_waitcnt lgkmcnt(11)
	v_add_f32_e32 v71, v71, v86
	s_waitcnt lgkmcnt(10)
	v_add_f32_e32 v72, v72, v87
	s_waitcnt lgkmcnt(9)
	v_add_f32_e32 v73, v73, v88
	s_waitcnt lgkmcnt(8)
	v_add_f32_e32 v74, v74, v89
	s_waitcnt lgkmcnt(7)
	v_add_f32_e32 v75, v75, v90
	s_waitcnt lgkmcnt(6)
	v_add_f32_e32 v76, v76, v91
	s_waitcnt lgkmcnt(5)
	v_add_f32_e32 v77, v77, v92
	s_waitcnt lgkmcnt(4)
	v_add_f32_e32 v78, v78, v93
	s_waitcnt lgkmcnt(3)
	v_add_f32_e32 v79, v79, v94
	s_waitcnt lgkmcnt(2)
	v_add_f32_e32 v80, v80, v95
	s_waitcnt lgkmcnt(1)
	v_add_f32_e32 v81, v81, v96
	s_waitcnt lgkmcnt(0)
	v_add_f32_e32 v82, v82, v97
	s_and_saveexec_b64 s[12:13], vcc
	v_mov_b32_e32 v98, s2
	ds_write_b32 v98, v68
	ds_write_b32 v98, v69 offset:4
	ds_write_b32 v98, v70 offset:8
	ds_write_b32 v98, v71 offset:12
	ds_write_b32 v98, v72 offset:16
	ds_write_b32 v98, v73 offset:20
	ds_write_b32 v98, v74 offset:24
	ds_write_b32 v98, v75 offset:28
	ds_write_b32 v98, v76 offset:32
	ds_write_b32 v98, v77 offset:36
	ds_write_b32 v98, v78 offset:40
	ds_write_b32 v98, v79 offset:44
	ds_write_b32 v98, v80 offset:48
	ds_write_b32 v98, v81 offset:52
	ds_write_b32 v98, v82 offset:56
	s_or_b64 exec, exec, s[12:13]
	v_fma_f32 v68, v21, v60, 0
	v_fmac_f32_e32 v68, v25, v61
	v_fma_f32 v69, v60, v10, 0
	v_fmac_f32_e32 v69, v61, v14
	v_fma_f32 v70, v60, v11, 0
	v_fmac_f32_e32 v70, v61, v15
	v_fma_f32 v71, v60, v12, 0
	v_fmac_f32_e32 v71, v61, v16
	v_fma_f32 v72, v60, v13, 0
	v_fmac_f32_e32 v72, v61, v17
	v_fma_f32 v73, v60, v2, 0
	v_fmac_f32_e32 v73, v61, v6
	v_fma_f32 v74, v60, v3, 0
	v_fmac_f32_e32 v74, v61, v7
	v_fma_f32 v75, v60, v4, 0
	v_fmac_f32_e32 v75, v61, v8
	v_fma_f32 v76, v60, v5, 0
	v_fmac_f32_e32 v76, v61, v9
	v_mul_f32_e32 v60, 0xbfb8aa3b, v58
	v_exp_f32_e32 v60, v60
	s_waitcnt lgkmcnt(0)
	v_mul_f32_e32 v61, 0xbfb8aa3b, v59
	v_exp_f32_e32 v61, v61
	v_add_f32_e32 v60, 1.0, v60
	v_rcp_f32_e32 v60, v60
	v_add_f32_e32 v61, 1.0, v61
	v_rcp_f32_e32 v61, v61
	v_mul_f32_e32 v58, v58, v60
	v_fma_f32 v77, v18, v58, 0
	v_mul_f32_e32 v59, v59, v61
	v_fmac_f32_e32 v77, v22, v59
	v_fma_f32 v78, v19, v58, 0
	v_fmac_f32_e32 v78, v23, v59
	v_fma_f32 v79, v20, v58, 0
	v_fmac_f32_e32 v79, v24, v59
	v_fma_f32 v80, v21, v58, 0
	v_fmac_f32_e32 v80, v25, v59
	v_fma_f32 v81, v10, v58, 0
	v_fmac_f32_e32 v81, v14, v59
	v_fma_f32 v82, v11, v58, 0
	v_fmac_f32_e32 v82, v15, v59
	ds_bpermute_b32 v83, v1, v68
	ds_bpermute_b32 v84, v1, v69
	ds_bpermute_b32 v85, v1, v70
	ds_bpermute_b32 v86, v1, v71
	ds_bpermute_b32 v87, v1, v72
	ds_bpermute_b32 v88, v1, v73
	ds_bpermute_b32 v89, v1, v74
	ds_bpermute_b32 v90, v1, v75
	ds_bpermute_b32 v91, v1, v76
	ds_bpermute_b32 v92, v1, v77
	ds_bpermute_b32 v93, v1, v78
	ds_bpermute_b32 v94, v1, v79
	ds_bpermute_b32 v95, v1, v80
	ds_bpermute_b32 v96, v1, v81
	ds_bpermute_b32 v97, v1, v82
	s_waitcnt lgkmcnt(14)
	v_add_f32_e32 v68, v68, v83
	s_waitcnt lgkmcnt(13)
	v_add_f32_e32 v69, v69, v84
	s_waitcnt lgkmcnt(12)
	v_add_f32_e32 v70, v70, v85
	s_waitcnt lgkmcnt(11)
	v_add_f32_e32 v71, v71, v86
	s_waitcnt lgkmcnt(10)
	v_add_f32_e32 v72, v72, v87
	s_waitcnt lgkmcnt(9)
	v_add_f32_e32 v73, v73, v88
	s_waitcnt lgkmcnt(8)
	v_add_f32_e32 v74, v74, v89
	s_waitcnt lgkmcnt(7)
	v_add_f32_e32 v75, v75, v90
	s_waitcnt lgkmcnt(6)
	v_add_f32_e32 v76, v76, v91
	s_waitcnt lgkmcnt(5)
	v_add_f32_e32 v77, v77, v92
	s_waitcnt lgkmcnt(4)
	v_add_f32_e32 v78, v78, v93
	s_waitcnt lgkmcnt(3)
	v_add_f32_e32 v79, v79, v94
	s_waitcnt lgkmcnt(2)
	v_add_f32_e32 v80, v80, v95
	s_waitcnt lgkmcnt(1)
	v_add_f32_e32 v81, v81, v96
	s_waitcnt lgkmcnt(0)
	v_add_f32_e32 v82, v82, v97
	ds_bpermute_b32 v83, v46, v68
	ds_bpermute_b32 v84, v46, v69
	ds_bpermute_b32 v85, v46, v70
	ds_bpermute_b32 v86, v46, v71
	ds_bpermute_b32 v87, v46, v72
	ds_bpermute_b32 v88, v46, v73
	ds_bpermute_b32 v89, v46, v74
	ds_bpermute_b32 v90, v46, v75
	ds_bpermute_b32 v91, v46, v76
	ds_bpermute_b32 v92, v46, v77
	ds_bpermute_b32 v93, v46, v78
	ds_bpermute_b32 v94, v46, v79
	ds_bpermute_b32 v95, v46, v80
	ds_bpermute_b32 v96, v46, v81
	ds_bpermute_b32 v97, v46, v82
	s_waitcnt lgkmcnt(14)
	v_add_f32_e32 v68, v68, v83
	s_waitcnt lgkmcnt(13)
	v_add_f32_e32 v69, v69, v84
	s_waitcnt lgkmcnt(12)
	v_add_f32_e32 v70, v70, v85
	s_waitcnt lgkmcnt(11)
	v_add_f32_e32 v71, v71, v86
	s_waitcnt lgkmcnt(10)
	v_add_f32_e32 v72, v72, v87
	s_waitcnt lgkmcnt(9)
	v_add_f32_e32 v73, v73, v88
	s_waitcnt lgkmcnt(8)
	v_add_f32_e32 v74, v74, v89
	s_waitcnt lgkmcnt(7)
	v_add_f32_e32 v75, v75, v90
	s_waitcnt lgkmcnt(6)
	v_add_f32_e32 v76, v76, v91
	s_waitcnt lgkmcnt(5)
	v_add_f32_e32 v77, v77, v92
	s_waitcnt lgkmcnt(4)
	v_add_f32_e32 v78, v78, v93
	s_waitcnt lgkmcnt(3)
	v_add_f32_e32 v79, v79, v94
	s_waitcnt lgkmcnt(2)
	v_add_f32_e32 v80, v80, v95
	s_waitcnt lgkmcnt(1)
	v_add_f32_e32 v81, v81, v96
	s_waitcnt lgkmcnt(0)
	v_add_f32_e32 v82, v82, v97
	ds_bpermute_b32 v83, v47, v68
	ds_bpermute_b32 v84, v47, v69
	ds_bpermute_b32 v85, v47, v70
	ds_bpermute_b32 v86, v47, v71
	ds_bpermute_b32 v87, v47, v72
	ds_bpermute_b32 v88, v47, v73
	ds_bpermute_b32 v89, v47, v74
	ds_bpermute_b32 v90, v47, v75
	ds_bpermute_b32 v91, v47, v76
	ds_bpermute_b32 v92, v47, v77
	ds_bpermute_b32 v93, v47, v78
	ds_bpermute_b32 v94, v47, v79
	ds_bpermute_b32 v95, v47, v80
	ds_bpermute_b32 v96, v47, v81
	ds_bpermute_b32 v97, v47, v82
	s_waitcnt lgkmcnt(14)
	v_add_f32_e32 v68, v68, v83
	s_waitcnt lgkmcnt(13)
	v_add_f32_e32 v69, v69, v84
	s_waitcnt lgkmcnt(12)
	v_add_f32_e32 v70, v70, v85
	s_waitcnt lgkmcnt(11)
	v_add_f32_e32 v71, v71, v86
	s_waitcnt lgkmcnt(10)
	v_add_f32_e32 v72, v72, v87
	s_waitcnt lgkmcnt(9)
	v_add_f32_e32 v73, v73, v88
	s_waitcnt lgkmcnt(8)
	v_add_f32_e32 v74, v74, v89
	s_waitcnt lgkmcnt(7)
	v_add_f32_e32 v75, v75, v90
	s_waitcnt lgkmcnt(6)
	v_add_f32_e32 v76, v76, v91
	s_waitcnt lgkmcnt(5)
	v_add_f32_e32 v77, v77, v92
	s_waitcnt lgkmcnt(4)
	v_add_f32_e32 v78, v78, v93
	s_waitcnt lgkmcnt(3)
	v_add_f32_e32 v79, v79, v94
	s_waitcnt lgkmcnt(2)
	v_add_f32_e32 v80, v80, v95
	s_waitcnt lgkmcnt(1)
	v_add_f32_e32 v81, v81, v96
	s_waitcnt lgkmcnt(0)
	v_add_f32_e32 v82, v82, v97
	ds_bpermute_b32 v83, v48, v68
	ds_bpermute_b32 v84, v48, v69
	ds_bpermute_b32 v85, v48, v70
	ds_bpermute_b32 v86, v48, v71
	ds_bpermute_b32 v87, v48, v72
	ds_bpermute_b32 v88, v48, v73
	ds_bpermute_b32 v89, v48, v74
	ds_bpermute_b32 v90, v48, v75
	ds_bpermute_b32 v91, v48, v76
	ds_bpermute_b32 v92, v48, v77
	ds_bpermute_b32 v93, v48, v78
	ds_bpermute_b32 v94, v48, v79
	ds_bpermute_b32 v95, v48, v80
	ds_bpermute_b32 v96, v48, v81
	ds_bpermute_b32 v97, v48, v82
	s_waitcnt lgkmcnt(14)
	v_add_f32_e32 v68, v68, v83
	s_waitcnt lgkmcnt(13)
	v_add_f32_e32 v69, v69, v84
	s_waitcnt lgkmcnt(12)
	v_add_f32_e32 v70, v70, v85
	s_waitcnt lgkmcnt(11)
	v_add_f32_e32 v71, v71, v86
	s_waitcnt lgkmcnt(10)
	v_add_f32_e32 v72, v72, v87
	s_waitcnt lgkmcnt(9)
	v_add_f32_e32 v73, v73, v88
	s_waitcnt lgkmcnt(8)
	v_add_f32_e32 v74, v74, v89
	s_waitcnt lgkmcnt(7)
	v_add_f32_e32 v75, v75, v90
	s_waitcnt lgkmcnt(6)
	v_add_f32_e32 v76, v76, v91
	s_waitcnt lgkmcnt(5)
	v_add_f32_e32 v77, v77, v92
	s_waitcnt lgkmcnt(4)
	v_add_f32_e32 v78, v78, v93
	s_waitcnt lgkmcnt(3)
	v_add_f32_e32 v79, v79, v94
	s_waitcnt lgkmcnt(2)
	v_add_f32_e32 v80, v80, v95
	s_waitcnt lgkmcnt(1)
	v_add_f32_e32 v81, v81, v96
	s_waitcnt lgkmcnt(0)
	v_add_f32_e32 v82, v82, v97
	ds_bpermute_b32 v83, v49, v68
	ds_bpermute_b32 v84, v49, v69
	ds_bpermute_b32 v85, v49, v70
	ds_bpermute_b32 v86, v49, v71
	ds_bpermute_b32 v87, v49, v72
	ds_bpermute_b32 v88, v49, v73
	ds_bpermute_b32 v89, v49, v74
	ds_bpermute_b32 v90, v49, v75
	ds_bpermute_b32 v91, v49, v76
	ds_bpermute_b32 v92, v49, v77
	ds_bpermute_b32 v93, v49, v78
	ds_bpermute_b32 v94, v49, v79
	ds_bpermute_b32 v95, v49, v80
	ds_bpermute_b32 v96, v49, v81
	ds_bpermute_b32 v97, v49, v82
	s_waitcnt lgkmcnt(14)
	v_add_f32_e32 v68, v68, v83
	s_waitcnt lgkmcnt(13)
	v_add_f32_e32 v69, v69, v84
	s_waitcnt lgkmcnt(12)
	v_add_f32_e32 v70, v70, v85
	s_waitcnt lgkmcnt(11)
	v_add_f32_e32 v71, v71, v86
	s_waitcnt lgkmcnt(10)
	v_add_f32_e32 v72, v72, v87
	s_waitcnt lgkmcnt(9)
	v_add_f32_e32 v73, v73, v88
	s_waitcnt lgkmcnt(8)
	v_add_f32_e32 v74, v74, v89
	s_waitcnt lgkmcnt(7)
	v_add_f32_e32 v75, v75, v90
	s_waitcnt lgkmcnt(6)
	v_add_f32_e32 v76, v76, v91
	s_waitcnt lgkmcnt(5)
	v_add_f32_e32 v77, v77, v92
	s_waitcnt lgkmcnt(4)
	v_add_f32_e32 v78, v78, v93
	s_waitcnt lgkmcnt(3)
	v_add_f32_e32 v79, v79, v94
	s_waitcnt lgkmcnt(2)
	v_add_f32_e32 v80, v80, v95
	s_waitcnt lgkmcnt(1)
	v_add_f32_e32 v81, v81, v96
	s_waitcnt lgkmcnt(0)
	v_add_f32_e32 v82, v82, v97
	ds_bpermute_b32 v83, v50, v68
	ds_bpermute_b32 v84, v50, v69
	ds_bpermute_b32 v85, v50, v70
	ds_bpermute_b32 v86, v50, v71
	ds_bpermute_b32 v87, v50, v72
	ds_bpermute_b32 v88, v50, v73
	ds_bpermute_b32 v89, v50, v74
	ds_bpermute_b32 v90, v50, v75
	ds_bpermute_b32 v91, v50, v76
	ds_bpermute_b32 v92, v50, v77
	ds_bpermute_b32 v93, v50, v78
	ds_bpermute_b32 v94, v50, v79
	ds_bpermute_b32 v95, v50, v80
	ds_bpermute_b32 v96, v50, v81
	ds_bpermute_b32 v97, v50, v82
	s_waitcnt lgkmcnt(14)
	v_add_f32_e32 v68, v68, v83
	s_waitcnt lgkmcnt(13)
	v_add_f32_e32 v69, v69, v84
	s_waitcnt lgkmcnt(12)
	v_add_f32_e32 v70, v70, v85
	s_waitcnt lgkmcnt(11)
	v_add_f32_e32 v71, v71, v86
	s_waitcnt lgkmcnt(10)
	v_add_f32_e32 v72, v72, v87
	s_waitcnt lgkmcnt(9)
	v_add_f32_e32 v73, v73, v88
	s_waitcnt lgkmcnt(8)
	v_add_f32_e32 v74, v74, v89
	s_waitcnt lgkmcnt(7)
	v_add_f32_e32 v75, v75, v90
	s_waitcnt lgkmcnt(6)
	v_add_f32_e32 v76, v76, v91
	s_waitcnt lgkmcnt(5)
	v_add_f32_e32 v77, v77, v92
	s_waitcnt lgkmcnt(4)
	v_add_f32_e32 v78, v78, v93
	s_waitcnt lgkmcnt(3)
	v_add_f32_e32 v79, v79, v94
	s_waitcnt lgkmcnt(2)
	v_add_f32_e32 v80, v80, v95
	s_waitcnt lgkmcnt(1)
	v_add_f32_e32 v81, v81, v96
	s_waitcnt lgkmcnt(0)
	v_add_f32_e32 v82, v82, v97
	s_and_saveexec_b64 s[12:13], vcc
	v_mov_b32_e32 v98, s2
	ds_write_b32 v98, v68 offset:60
	ds_write_b32 v98, v69 offset:64
	ds_write_b32 v98, v70 offset:68
	ds_write_b32 v98, v71 offset:72
	ds_write_b32 v98, v72 offset:76
	ds_write_b32 v98, v73 offset:80
	ds_write_b32 v98, v74 offset:84
	ds_write_b32 v98, v75 offset:88
	ds_write_b32 v98, v76 offset:92
	ds_write_b32 v98, v77 offset:96
	ds_write_b32 v98, v78 offset:100
	ds_write_b32 v98, v79 offset:104
	ds_write_b32 v98, v80 offset:108
	ds_write_b32 v98, v81 offset:112
	ds_write_b32 v98, v82 offset:116
	s_or_b64 exec, exec, s[12:13]
	v_fma_f32 v68, v12, v58, 0
	v_fmac_f32_e32 v68, v16, v59
	v_fma_f32 v69, v13, v58, 0
	v_fmac_f32_e32 v69, v17, v59
	v_fma_f32 v70, v58, v2, 0
	v_fmac_f32_e32 v70, v59, v6
	v_fma_f32 v71, v58, v3, 0
	v_fmac_f32_e32 v71, v59, v7
	v_fma_f32 v72, v58, v4, 0
	v_fmac_f32_e32 v72, v59, v8
	v_fma_f32 v73, v58, v5, 0
	v_fmac_f32_e32 v73, v59, v9
	v_mul_f32_e32 v58, 0xbfb8aa3b, v56
	v_exp_f32_e32 v58, v58
	s_waitcnt lgkmcnt(0)
	v_mul_f32_e32 v59, 0xbfb8aa3b, v57
	v_exp_f32_e32 v59, v59
	v_add_f32_e32 v58, 1.0, v58
	v_rcp_f32_e32 v58, v58
	v_add_f32_e32 v59, 1.0, v59
	v_rcp_f32_e32 v59, v59
	v_mul_f32_e32 v56, v56, v58
	v_fma_f32 v74, v18, v56, 0
	v_mul_f32_e32 v57, v57, v59
	v_fmac_f32_e32 v74, v22, v57
	v_fma_f32 v75, v19, v56, 0
	v_fmac_f32_e32 v75, v23, v57
	v_fma_f32 v76, v20, v56, 0
	v_fmac_f32_e32 v76, v24, v57
	v_fma_f32 v77, v21, v56, 0
	v_fmac_f32_e32 v77, v25, v57
	v_fma_f32 v78, v10, v56, 0
	v_fmac_f32_e32 v78, v14, v57
	v_fma_f32 v79, v11, v56, 0
	v_fmac_f32_e32 v79, v15, v57
	v_fma_f32 v80, v12, v56, 0
	v_fmac_f32_e32 v80, v16, v57
	v_fma_f32 v81, v13, v56, 0
	v_fmac_f32_e32 v81, v17, v57
	v_fma_f32 v82, v2, v56, 0
	v_fmac_f32_e32 v82, v6, v57
	ds_bpermute_b32 v83, v1, v68
	ds_bpermute_b32 v84, v1, v69
	ds_bpermute_b32 v85, v1, v70
	ds_bpermute_b32 v86, v1, v71
	ds_bpermute_b32 v87, v1, v72
	ds_bpermute_b32 v88, v1, v73
	ds_bpermute_b32 v89, v1, v74
	ds_bpermute_b32 v90, v1, v75
	ds_bpermute_b32 v91, v1, v76
	ds_bpermute_b32 v92, v1, v77
	ds_bpermute_b32 v93, v1, v78
	ds_bpermute_b32 v94, v1, v79
	ds_bpermute_b32 v95, v1, v80
	ds_bpermute_b32 v96, v1, v81
	ds_bpermute_b32 v97, v1, v82
	s_waitcnt lgkmcnt(14)
	v_add_f32_e32 v68, v68, v83
	s_waitcnt lgkmcnt(13)
	v_add_f32_e32 v69, v69, v84
	s_waitcnt lgkmcnt(12)
	v_add_f32_e32 v70, v70, v85
	s_waitcnt lgkmcnt(11)
	v_add_f32_e32 v71, v71, v86
	s_waitcnt lgkmcnt(10)
	v_add_f32_e32 v72, v72, v87
	s_waitcnt lgkmcnt(9)
	v_add_f32_e32 v73, v73, v88
	s_waitcnt lgkmcnt(8)
	v_add_f32_e32 v74, v74, v89
	s_waitcnt lgkmcnt(7)
	v_add_f32_e32 v75, v75, v90
	s_waitcnt lgkmcnt(6)
	v_add_f32_e32 v76, v76, v91
	s_waitcnt lgkmcnt(5)
	v_add_f32_e32 v77, v77, v92
	s_waitcnt lgkmcnt(4)
	v_add_f32_e32 v78, v78, v93
	s_waitcnt lgkmcnt(3)
	v_add_f32_e32 v79, v79, v94
	s_waitcnt lgkmcnt(2)
	v_add_f32_e32 v80, v80, v95
	s_waitcnt lgkmcnt(1)
	v_add_f32_e32 v81, v81, v96
	s_waitcnt lgkmcnt(0)
	v_add_f32_e32 v82, v82, v97
	ds_bpermute_b32 v83, v46, v68
	ds_bpermute_b32 v84, v46, v69
	ds_bpermute_b32 v85, v46, v70
	ds_bpermute_b32 v86, v46, v71
	ds_bpermute_b32 v87, v46, v72
	ds_bpermute_b32 v88, v46, v73
	ds_bpermute_b32 v89, v46, v74
	ds_bpermute_b32 v90, v46, v75
	ds_bpermute_b32 v91, v46, v76
	ds_bpermute_b32 v92, v46, v77
	ds_bpermute_b32 v93, v46, v78
	ds_bpermute_b32 v94, v46, v79
	ds_bpermute_b32 v95, v46, v80
	ds_bpermute_b32 v96, v46, v81
	ds_bpermute_b32 v97, v46, v82
	s_waitcnt lgkmcnt(14)
	v_add_f32_e32 v68, v68, v83
	s_waitcnt lgkmcnt(13)
	v_add_f32_e32 v69, v69, v84
	s_waitcnt lgkmcnt(12)
	v_add_f32_e32 v70, v70, v85
	s_waitcnt lgkmcnt(11)
	v_add_f32_e32 v71, v71, v86
	s_waitcnt lgkmcnt(10)
	v_add_f32_e32 v72, v72, v87
	s_waitcnt lgkmcnt(9)
	v_add_f32_e32 v73, v73, v88
	s_waitcnt lgkmcnt(8)
	v_add_f32_e32 v74, v74, v89
	s_waitcnt lgkmcnt(7)
	v_add_f32_e32 v75, v75, v90
	s_waitcnt lgkmcnt(6)
	v_add_f32_e32 v76, v76, v91
	s_waitcnt lgkmcnt(5)
	v_add_f32_e32 v77, v77, v92
	s_waitcnt lgkmcnt(4)
	v_add_f32_e32 v78, v78, v93
	s_waitcnt lgkmcnt(3)
	v_add_f32_e32 v79, v79, v94
	s_waitcnt lgkmcnt(2)
	v_add_f32_e32 v80, v80, v95
	s_waitcnt lgkmcnt(1)
	v_add_f32_e32 v81, v81, v96
	s_waitcnt lgkmcnt(0)
	v_add_f32_e32 v82, v82, v97
	ds_bpermute_b32 v83, v47, v68
	ds_bpermute_b32 v84, v47, v69
	ds_bpermute_b32 v85, v47, v70
	ds_bpermute_b32 v86, v47, v71
	ds_bpermute_b32 v87, v47, v72
	ds_bpermute_b32 v88, v47, v73
	ds_bpermute_b32 v89, v47, v74
	ds_bpermute_b32 v90, v47, v75
	ds_bpermute_b32 v91, v47, v76
	ds_bpermute_b32 v92, v47, v77
	ds_bpermute_b32 v93, v47, v78
	ds_bpermute_b32 v94, v47, v79
	ds_bpermute_b32 v95, v47, v80
	ds_bpermute_b32 v96, v47, v81
	ds_bpermute_b32 v97, v47, v82
	s_waitcnt lgkmcnt(14)
	v_add_f32_e32 v68, v68, v83
	s_waitcnt lgkmcnt(13)
	v_add_f32_e32 v69, v69, v84
	s_waitcnt lgkmcnt(12)
	v_add_f32_e32 v70, v70, v85
	s_waitcnt lgkmcnt(11)
	v_add_f32_e32 v71, v71, v86
	s_waitcnt lgkmcnt(10)
	v_add_f32_e32 v72, v72, v87
	s_waitcnt lgkmcnt(9)
	v_add_f32_e32 v73, v73, v88
	s_waitcnt lgkmcnt(8)
	v_add_f32_e32 v74, v74, v89
	s_waitcnt lgkmcnt(7)
	v_add_f32_e32 v75, v75, v90
	s_waitcnt lgkmcnt(6)
	v_add_f32_e32 v76, v76, v91
	s_waitcnt lgkmcnt(5)
	v_add_f32_e32 v77, v77, v92
	s_waitcnt lgkmcnt(4)
	v_add_f32_e32 v78, v78, v93
	s_waitcnt lgkmcnt(3)
	v_add_f32_e32 v79, v79, v94
	s_waitcnt lgkmcnt(2)
	v_add_f32_e32 v80, v80, v95
	s_waitcnt lgkmcnt(1)
	v_add_f32_e32 v81, v81, v96
	s_waitcnt lgkmcnt(0)
	v_add_f32_e32 v82, v82, v97
	ds_bpermute_b32 v83, v48, v68
	ds_bpermute_b32 v84, v48, v69
	ds_bpermute_b32 v85, v48, v70
	ds_bpermute_b32 v86, v48, v71
	ds_bpermute_b32 v87, v48, v72
	ds_bpermute_b32 v88, v48, v73
	ds_bpermute_b32 v89, v48, v74
	ds_bpermute_b32 v90, v48, v75
	ds_bpermute_b32 v91, v48, v76
	ds_bpermute_b32 v92, v48, v77
	ds_bpermute_b32 v93, v48, v78
	ds_bpermute_b32 v94, v48, v79
	ds_bpermute_b32 v95, v48, v80
	ds_bpermute_b32 v96, v48, v81
	ds_bpermute_b32 v97, v48, v82
	s_waitcnt lgkmcnt(14)
	v_add_f32_e32 v68, v68, v83
	s_waitcnt lgkmcnt(13)
	v_add_f32_e32 v69, v69, v84
	s_waitcnt lgkmcnt(12)
	v_add_f32_e32 v70, v70, v85
	s_waitcnt lgkmcnt(11)
	v_add_f32_e32 v71, v71, v86
	s_waitcnt lgkmcnt(10)
	v_add_f32_e32 v72, v72, v87
	s_waitcnt lgkmcnt(9)
	v_add_f32_e32 v73, v73, v88
	s_waitcnt lgkmcnt(8)
	v_add_f32_e32 v74, v74, v89
	s_waitcnt lgkmcnt(7)
	v_add_f32_e32 v75, v75, v90
	s_waitcnt lgkmcnt(6)
	v_add_f32_e32 v76, v76, v91
	s_waitcnt lgkmcnt(5)
	v_add_f32_e32 v77, v77, v92
	s_waitcnt lgkmcnt(4)
	v_add_f32_e32 v78, v78, v93
	s_waitcnt lgkmcnt(3)
	v_add_f32_e32 v79, v79, v94
	s_waitcnt lgkmcnt(2)
	v_add_f32_e32 v80, v80, v95
	s_waitcnt lgkmcnt(1)
	v_add_f32_e32 v81, v81, v96
	s_waitcnt lgkmcnt(0)
	v_add_f32_e32 v82, v82, v97
	ds_bpermute_b32 v83, v49, v68
	ds_bpermute_b32 v84, v49, v69
	ds_bpermute_b32 v85, v49, v70
	ds_bpermute_b32 v86, v49, v71
	ds_bpermute_b32 v87, v49, v72
	ds_bpermute_b32 v88, v49, v73
	ds_bpermute_b32 v89, v49, v74
	ds_bpermute_b32 v90, v49, v75
	ds_bpermute_b32 v91, v49, v76
	ds_bpermute_b32 v92, v49, v77
	ds_bpermute_b32 v93, v49, v78
	ds_bpermute_b32 v94, v49, v79
	ds_bpermute_b32 v95, v49, v80
	ds_bpermute_b32 v96, v49, v81
	ds_bpermute_b32 v97, v49, v82
	s_waitcnt lgkmcnt(14)
	v_add_f32_e32 v68, v68, v83
	s_waitcnt lgkmcnt(13)
	v_add_f32_e32 v69, v69, v84
	s_waitcnt lgkmcnt(12)
	v_add_f32_e32 v70, v70, v85
	s_waitcnt lgkmcnt(11)
	v_add_f32_e32 v71, v71, v86
	s_waitcnt lgkmcnt(10)
	v_add_f32_e32 v72, v72, v87
	s_waitcnt lgkmcnt(9)
	v_add_f32_e32 v73, v73, v88
	s_waitcnt lgkmcnt(8)
	v_add_f32_e32 v74, v74, v89
	s_waitcnt lgkmcnt(7)
	v_add_f32_e32 v75, v75, v90
	s_waitcnt lgkmcnt(6)
	v_add_f32_e32 v76, v76, v91
	s_waitcnt lgkmcnt(5)
	v_add_f32_e32 v77, v77, v92
	s_waitcnt lgkmcnt(4)
	v_add_f32_e32 v78, v78, v93
	s_waitcnt lgkmcnt(3)
	v_add_f32_e32 v79, v79, v94
	s_waitcnt lgkmcnt(2)
	v_add_f32_e32 v80, v80, v95
	s_waitcnt lgkmcnt(1)
	v_add_f32_e32 v81, v81, v96
	s_waitcnt lgkmcnt(0)
	v_add_f32_e32 v82, v82, v97
	ds_bpermute_b32 v83, v50, v68
	ds_bpermute_b32 v84, v50, v69
	ds_bpermute_b32 v85, v50, v70
	ds_bpermute_b32 v86, v50, v71
	ds_bpermute_b32 v87, v50, v72
	ds_bpermute_b32 v88, v50, v73
	ds_bpermute_b32 v89, v50, v74
	ds_bpermute_b32 v90, v50, v75
	ds_bpermute_b32 v91, v50, v76
	ds_bpermute_b32 v92, v50, v77
	ds_bpermute_b32 v93, v50, v78
	ds_bpermute_b32 v94, v50, v79
	ds_bpermute_b32 v95, v50, v80
	ds_bpermute_b32 v96, v50, v81
	ds_bpermute_b32 v97, v50, v82
	s_waitcnt lgkmcnt(14)
	v_add_f32_e32 v68, v68, v83
	s_waitcnt lgkmcnt(13)
	v_add_f32_e32 v69, v69, v84
	s_waitcnt lgkmcnt(12)
	v_add_f32_e32 v70, v70, v85
	s_waitcnt lgkmcnt(11)
	v_add_f32_e32 v71, v71, v86
	s_waitcnt lgkmcnt(10)
	v_add_f32_e32 v72, v72, v87
	s_waitcnt lgkmcnt(9)
	v_add_f32_e32 v73, v73, v88
	s_waitcnt lgkmcnt(8)
	v_add_f32_e32 v74, v74, v89
	s_waitcnt lgkmcnt(7)
	v_add_f32_e32 v75, v75, v90
	s_waitcnt lgkmcnt(6)
	v_add_f32_e32 v76, v76, v91
	s_waitcnt lgkmcnt(5)
	v_add_f32_e32 v77, v77, v92
	s_waitcnt lgkmcnt(4)
	v_add_f32_e32 v78, v78, v93
	s_waitcnt lgkmcnt(3)
	v_add_f32_e32 v79, v79, v94
	s_waitcnt lgkmcnt(2)
	v_add_f32_e32 v80, v80, v95
	s_waitcnt lgkmcnt(1)
	v_add_f32_e32 v81, v81, v96
	s_waitcnt lgkmcnt(0)
	v_add_f32_e32 v82, v82, v97
	s_and_saveexec_b64 s[12:13], vcc
	v_mov_b32_e32 v98, s2
	ds_write_b32 v98, v68 offset:120
	ds_write_b32 v98, v69 offset:124
	ds_write_b32 v98, v70 offset:128
	ds_write_b32 v98, v71 offset:132
	ds_write_b32 v98, v72 offset:136
	ds_write_b32 v98, v73 offset:140
	ds_write_b32 v98, v74 offset:144
	ds_write_b32 v98, v75 offset:148
	ds_write_b32 v98, v76 offset:152
	ds_write_b32 v98, v77 offset:156
	ds_write_b32 v98, v78 offset:160
	ds_write_b32 v98, v79 offset:164
	ds_write_b32 v98, v80 offset:168
	ds_write_b32 v98, v81 offset:172
	ds_write_b32 v98, v82 offset:176
	s_or_b64 exec, exec, s[12:13]
	v_fma_f32 v68, v3, v56, 0
	v_fmac_f32_e32 v68, v7, v57
	v_fma_f32 v69, v4, v56, 0
	v_fmac_f32_e32 v69, v8, v57
	v_fma_f32 v70, v5, v56, 0
	v_fmac_f32_e32 v70, v9, v57
	v_mul_f32_e32 v56, 0xbfb8aa3b, v55
	v_exp_f32_e32 v56, v56
	s_waitcnt lgkmcnt(0)
	v_mul_f32_e32 v57, 0xbfb8aa3b, v54
	v_exp_f32_e32 v57, v57
	v_add_f32_e32 v56, 1.0, v56
	v_rcp_f32_e32 v56, v56
	v_add_f32_e32 v57, 1.0, v57
	v_rcp_f32_e32 v57, v57
	v_mul_f32_e32 v55, v55, v56
	v_fma_f32 v71, v18, v55, 0
	v_mul_f32_e32 v18, v54, v57
	v_fmac_f32_e32 v71, v22, v18
	v_fma_f32 v72, v19, v55, 0
	v_fmac_f32_e32 v72, v23, v18
	v_fma_f32 v73, v20, v55, 0
	v_fmac_f32_e32 v73, v24, v18
	v_fma_f32 v74, v21, v55, 0
	v_fmac_f32_e32 v74, v25, v18
	v_fma_f32 v75, v10, v55, 0
	v_fmac_f32_e32 v75, v14, v18
	v_fma_f32 v76, v11, v55, 0
	v_fmac_f32_e32 v76, v15, v18
	v_fma_f32 v77, v12, v55, 0
	v_fmac_f32_e32 v77, v16, v18
	v_fma_f32 v78, v13, v55, 0
	v_fmac_f32_e32 v78, v17, v18
	v_fma_f32 v79, v2, v55, 0
	v_fmac_f32_e32 v79, v6, v18
	v_fma_f32 v80, v3, v55, 0
	v_fmac_f32_e32 v80, v7, v18
	v_fma_f32 v81, v4, v55, 0
	v_fmac_f32_e32 v81, v8, v18
	v_fma_f32 v82, v5, v55, 0
	v_fmac_f32_e32 v82, v9, v18
	ds_bpermute_b32 v83, v1, v68
	ds_bpermute_b32 v84, v1, v69
	ds_bpermute_b32 v85, v1, v70
	ds_bpermute_b32 v86, v1, v71
	ds_bpermute_b32 v87, v1, v72
	ds_bpermute_b32 v88, v1, v73
	ds_bpermute_b32 v89, v1, v74
	ds_bpermute_b32 v90, v1, v75
	ds_bpermute_b32 v91, v1, v76
	ds_bpermute_b32 v92, v1, v77
	ds_bpermute_b32 v93, v1, v78
	ds_bpermute_b32 v94, v1, v79
	ds_bpermute_b32 v95, v1, v80
	ds_bpermute_b32 v96, v1, v81
	ds_bpermute_b32 v97, v1, v82
	s_waitcnt lgkmcnt(14)
	v_add_f32_e32 v68, v68, v83
	s_waitcnt lgkmcnt(13)
	v_add_f32_e32 v69, v69, v84
	s_waitcnt lgkmcnt(12)
	v_add_f32_e32 v70, v70, v85
	s_waitcnt lgkmcnt(11)
	v_add_f32_e32 v71, v71, v86
	s_waitcnt lgkmcnt(10)
	v_add_f32_e32 v72, v72, v87
	s_waitcnt lgkmcnt(9)
	v_add_f32_e32 v73, v73, v88
	s_waitcnt lgkmcnt(8)
	v_add_f32_e32 v74, v74, v89
	s_waitcnt lgkmcnt(7)
	v_add_f32_e32 v75, v75, v90
	s_waitcnt lgkmcnt(6)
	v_add_f32_e32 v76, v76, v91
	s_waitcnt lgkmcnt(5)
	v_add_f32_e32 v77, v77, v92
	s_waitcnt lgkmcnt(4)
	v_add_f32_e32 v78, v78, v93
	s_waitcnt lgkmcnt(3)
	v_add_f32_e32 v79, v79, v94
	s_waitcnt lgkmcnt(2)
	v_add_f32_e32 v80, v80, v95
	s_waitcnt lgkmcnt(1)
	v_add_f32_e32 v81, v81, v96
	s_waitcnt lgkmcnt(0)
	v_add_f32_e32 v82, v82, v97
	ds_bpermute_b32 v83, v46, v68
	ds_bpermute_b32 v84, v46, v69
	ds_bpermute_b32 v85, v46, v70
	ds_bpermute_b32 v86, v46, v71
	ds_bpermute_b32 v87, v46, v72
	ds_bpermute_b32 v88, v46, v73
	ds_bpermute_b32 v89, v46, v74
	ds_bpermute_b32 v90, v46, v75
	ds_bpermute_b32 v91, v46, v76
	ds_bpermute_b32 v92, v46, v77
	ds_bpermute_b32 v93, v46, v78
	ds_bpermute_b32 v94, v46, v79
	ds_bpermute_b32 v95, v46, v80
	ds_bpermute_b32 v96, v46, v81
	ds_bpermute_b32 v97, v46, v82
	s_waitcnt lgkmcnt(14)
	v_add_f32_e32 v68, v68, v83
	s_waitcnt lgkmcnt(13)
	v_add_f32_e32 v69, v69, v84
	s_waitcnt lgkmcnt(12)
	v_add_f32_e32 v70, v70, v85
	s_waitcnt lgkmcnt(11)
	v_add_f32_e32 v71, v71, v86
	s_waitcnt lgkmcnt(10)
	v_add_f32_e32 v72, v72, v87
	s_waitcnt lgkmcnt(9)
	v_add_f32_e32 v73, v73, v88
	s_waitcnt lgkmcnt(8)
	v_add_f32_e32 v74, v74, v89
	s_waitcnt lgkmcnt(7)
	v_add_f32_e32 v75, v75, v90
	s_waitcnt lgkmcnt(6)
	v_add_f32_e32 v76, v76, v91
	s_waitcnt lgkmcnt(5)
	v_add_f32_e32 v77, v77, v92
	s_waitcnt lgkmcnt(4)
	v_add_f32_e32 v78, v78, v93
	s_waitcnt lgkmcnt(3)
	v_add_f32_e32 v79, v79, v94
	s_waitcnt lgkmcnt(2)
	v_add_f32_e32 v80, v80, v95
	s_waitcnt lgkmcnt(1)
	v_add_f32_e32 v81, v81, v96
	s_waitcnt lgkmcnt(0)
	v_add_f32_e32 v82, v82, v97
	ds_bpermute_b32 v83, v47, v68
	ds_bpermute_b32 v84, v47, v69
	ds_bpermute_b32 v85, v47, v70
	ds_bpermute_b32 v86, v47, v71
	ds_bpermute_b32 v87, v47, v72
	ds_bpermute_b32 v88, v47, v73
	ds_bpermute_b32 v89, v47, v74
	ds_bpermute_b32 v90, v47, v75
	ds_bpermute_b32 v91, v47, v76
	ds_bpermute_b32 v92, v47, v77
	ds_bpermute_b32 v93, v47, v78
	ds_bpermute_b32 v94, v47, v79
	ds_bpermute_b32 v95, v47, v80
	ds_bpermute_b32 v96, v47, v81
	ds_bpermute_b32 v97, v47, v82
	s_waitcnt lgkmcnt(14)
	v_add_f32_e32 v68, v68, v83
	s_waitcnt lgkmcnt(13)
	v_add_f32_e32 v69, v69, v84
	s_waitcnt lgkmcnt(12)
	v_add_f32_e32 v70, v70, v85
	s_waitcnt lgkmcnt(11)
	v_add_f32_e32 v71, v71, v86
	s_waitcnt lgkmcnt(10)
	v_add_f32_e32 v72, v72, v87
	s_waitcnt lgkmcnt(9)
	v_add_f32_e32 v73, v73, v88
	s_waitcnt lgkmcnt(8)
	v_add_f32_e32 v74, v74, v89
	s_waitcnt lgkmcnt(7)
	v_add_f32_e32 v75, v75, v90
	s_waitcnt lgkmcnt(6)
	v_add_f32_e32 v76, v76, v91
	s_waitcnt lgkmcnt(5)
	v_add_f32_e32 v77, v77, v92
	s_waitcnt lgkmcnt(4)
	v_add_f32_e32 v78, v78, v93
	s_waitcnt lgkmcnt(3)
	v_add_f32_e32 v79, v79, v94
	s_waitcnt lgkmcnt(2)
	v_add_f32_e32 v80, v80, v95
	s_waitcnt lgkmcnt(1)
	v_add_f32_e32 v81, v81, v96
	s_waitcnt lgkmcnt(0)
	v_add_f32_e32 v82, v82, v97
	ds_bpermute_b32 v83, v48, v68
	ds_bpermute_b32 v84, v48, v69
	ds_bpermute_b32 v85, v48, v70
	ds_bpermute_b32 v86, v48, v71
	ds_bpermute_b32 v87, v48, v72
	ds_bpermute_b32 v88, v48, v73
	ds_bpermute_b32 v89, v48, v74
	ds_bpermute_b32 v90, v48, v75
	ds_bpermute_b32 v91, v48, v76
	ds_bpermute_b32 v92, v48, v77
	ds_bpermute_b32 v93, v48, v78
	ds_bpermute_b32 v94, v48, v79
	ds_bpermute_b32 v95, v48, v80
	ds_bpermute_b32 v96, v48, v81
	ds_bpermute_b32 v97, v48, v82
	s_waitcnt lgkmcnt(14)
	v_add_f32_e32 v68, v68, v83
	s_waitcnt lgkmcnt(13)
	v_add_f32_e32 v69, v69, v84
	s_waitcnt lgkmcnt(12)
	v_add_f32_e32 v70, v70, v85
	s_waitcnt lgkmcnt(11)
	v_add_f32_e32 v71, v71, v86
	s_waitcnt lgkmcnt(10)
	v_add_f32_e32 v72, v72, v87
	s_waitcnt lgkmcnt(9)
	v_add_f32_e32 v73, v73, v88
	s_waitcnt lgkmcnt(8)
	v_add_f32_e32 v74, v74, v89
	s_waitcnt lgkmcnt(7)
	v_add_f32_e32 v75, v75, v90
	s_waitcnt lgkmcnt(6)
	v_add_f32_e32 v76, v76, v91
	s_waitcnt lgkmcnt(5)
	v_add_f32_e32 v77, v77, v92
	s_waitcnt lgkmcnt(4)
	v_add_f32_e32 v78, v78, v93
	s_waitcnt lgkmcnt(3)
	v_add_f32_e32 v79, v79, v94
	s_waitcnt lgkmcnt(2)
	v_add_f32_e32 v80, v80, v95
	s_waitcnt lgkmcnt(1)
	v_add_f32_e32 v81, v81, v96
	s_waitcnt lgkmcnt(0)
	v_add_f32_e32 v82, v82, v97
	ds_bpermute_b32 v83, v49, v68
	ds_bpermute_b32 v84, v49, v69
	ds_bpermute_b32 v85, v49, v70
	ds_bpermute_b32 v86, v49, v71
	ds_bpermute_b32 v87, v49, v72
	ds_bpermute_b32 v88, v49, v73
	ds_bpermute_b32 v89, v49, v74
	ds_bpermute_b32 v90, v49, v75
	ds_bpermute_b32 v91, v49, v76
	ds_bpermute_b32 v92, v49, v77
	ds_bpermute_b32 v93, v49, v78
	ds_bpermute_b32 v94, v49, v79
	ds_bpermute_b32 v95, v49, v80
	ds_bpermute_b32 v96, v49, v81
	ds_bpermute_b32 v97, v49, v82
	s_waitcnt lgkmcnt(14)
	v_add_f32_e32 v68, v68, v83
	s_waitcnt lgkmcnt(13)
	v_add_f32_e32 v69, v69, v84
	s_waitcnt lgkmcnt(12)
	v_add_f32_e32 v70, v70, v85
	s_waitcnt lgkmcnt(11)
	v_add_f32_e32 v71, v71, v86
	s_waitcnt lgkmcnt(10)
	v_add_f32_e32 v72, v72, v87
	s_waitcnt lgkmcnt(9)
	v_add_f32_e32 v73, v73, v88
	s_waitcnt lgkmcnt(8)
	v_add_f32_e32 v74, v74, v89
	s_waitcnt lgkmcnt(7)
	v_add_f32_e32 v75, v75, v90
	s_waitcnt lgkmcnt(6)
	v_add_f32_e32 v76, v76, v91
	s_waitcnt lgkmcnt(5)
	v_add_f32_e32 v77, v77, v92
	s_waitcnt lgkmcnt(4)
	v_add_f32_e32 v78, v78, v93
	s_waitcnt lgkmcnt(3)
	v_add_f32_e32 v79, v79, v94
	s_waitcnt lgkmcnt(2)
	v_add_f32_e32 v80, v80, v95
	s_waitcnt lgkmcnt(1)
	v_add_f32_e32 v81, v81, v96
	s_waitcnt lgkmcnt(0)
	v_add_f32_e32 v82, v82, v97
	ds_bpermute_b32 v83, v50, v68
	ds_bpermute_b32 v84, v50, v69
	ds_bpermute_b32 v85, v50, v70
	ds_bpermute_b32 v86, v50, v71
	ds_bpermute_b32 v87, v50, v72
	ds_bpermute_b32 v88, v50, v73
	ds_bpermute_b32 v89, v50, v74
	ds_bpermute_b32 v90, v50, v75
	ds_bpermute_b32 v91, v50, v76
	ds_bpermute_b32 v92, v50, v77
	ds_bpermute_b32 v93, v50, v78
	ds_bpermute_b32 v94, v50, v79
	ds_bpermute_b32 v95, v50, v80
	ds_bpermute_b32 v96, v50, v81
	ds_bpermute_b32 v97, v50, v82
	s_waitcnt lgkmcnt(14)
	v_add_f32_e32 v68, v68, v83
	s_waitcnt lgkmcnt(13)
	v_add_f32_e32 v69, v69, v84
	s_waitcnt lgkmcnt(12)
	v_add_f32_e32 v70, v70, v85
	s_waitcnt lgkmcnt(11)
	v_add_f32_e32 v71, v71, v86
	s_waitcnt lgkmcnt(10)
	v_add_f32_e32 v72, v72, v87
	s_waitcnt lgkmcnt(9)
	v_add_f32_e32 v73, v73, v88
	s_waitcnt lgkmcnt(8)
	v_add_f32_e32 v74, v74, v89
	s_waitcnt lgkmcnt(7)
	v_add_f32_e32 v75, v75, v90
	s_waitcnt lgkmcnt(6)
	v_add_f32_e32 v76, v76, v91
	s_waitcnt lgkmcnt(5)
	v_add_f32_e32 v77, v77, v92
	s_waitcnt lgkmcnt(4)
	v_add_f32_e32 v78, v78, v93
	s_waitcnt lgkmcnt(3)
	v_add_f32_e32 v79, v79, v94
	s_waitcnt lgkmcnt(2)
	v_add_f32_e32 v80, v80, v95
	s_waitcnt lgkmcnt(1)
	v_add_f32_e32 v81, v81, v96
	s_waitcnt lgkmcnt(0)
	v_add_f32_e32 v82, v82, v97
	s_and_saveexec_b64 s[12:13], vcc
	v_mov_b32_e32 v98, s2
	ds_write_b32 v98, v68 offset:180
	ds_write_b32 v98, v69 offset:184
	ds_write_b32 v98, v70 offset:188
	ds_write_b32 v98, v71 offset:192
	ds_write_b32 v98, v72 offset:196
	ds_write_b32 v98, v73 offset:200
	ds_write_b32 v98, v74 offset:204
	ds_write_b32 v98, v75 offset:208
	ds_write_b32 v98, v76 offset:212
	ds_write_b32 v98, v77 offset:216
	ds_write_b32 v98, v78 offset:220
	ds_write_b32 v98, v79 offset:224
	ds_write_b32 v98, v80 offset:228
	ds_write_b32 v98, v81 offset:232
	ds_write_b32 v98, v82 offset:236
	s_or_b64 exec, exec, s[12:13]

.LBB0_2232:
	s_or_b64 exec, exec, s[4:5]
	s_waitcnt vmcnt(0) lgkmcnt(0)
	s_barrier
	s_mov_b32 s98, 0xaaaaaaaa
	s_mov_b32 s99, 0xaaaaaaaa
	v_mov_b32_e32 v244, 0xfffff010
	v_mov_b32_e32 v245, 0x1000
	v_cndmask_b32_e64 v240, 0, v244, s[98:99]
	v_cndmask_b32_e64 v241, 0, -1, s[98:99]
	v_cndmask_b32_e64 v242, v245, 16, s[98:99]
	v_mov_b32_e32 v243, 0
	v_lshl_add_u64 v[0:1], v[194:195], 2, s[76:77]
	global_load_dwordx4 v[12:15], v[0:1], off
	global_load_dwordx4 v[8:11], v[0:1], off offset:16
	global_load_dwordx4 v[4:7], v[0:1], off offset:512
	s_waitcnt lgkmcnt(0)
	global_load_dwordx4 v[0:3], v[0:1], off offset:528
	v_lshl_add_u32 v84, v199, 2, 0
	v_add_u32_e32 v142, 0x1000, v84
	v_add_u32_e32 v76, s21, v199
	ds_read2_b32 v[88:89], v142 offset1:16
	v_mov_b32_e32 v77, s12
	v_add_u32_e32 v84, 16, v76
	v_add_u32_e32 v86, 32, v76
	ds_read2_b32 v[134:135], v142 offset0:32 offset1:48
	v_or3_b32 v82, s20, v202, v77
	v_ashrrev_i32_e32 v77, 31, v76
	v_ashrrev_i32_e32 v85, 31, v84
	v_ashrrev_i32_e32 v87, 31, v86
	v_or3_b32 v83, 0, 0, s13
	v_lshlrev_b64 v[90:91], 12, v[76:77]
	v_lshlrev_b64 v[84:85], 12, v[84:85]
	v_lshlrev_b64 v[86:87], 12, v[86:87]
	v_lshlrev_b64 v[82:83], 2, v[82:83]
	v_lshl_add_u64 v[90:91], s[78:79], 0, v[90:91]
	v_lshl_add_u64 v[84:85], s[78:79], 0, v[84:85]
	v_lshl_add_u64 v[86:87], s[78:79], 0, v[86:87]
	v_lshl_add_u64 v[136:137], v[90:91], 0, v[82:83]
	v_lshl_add_u64 v[138:139], v[84:85], 0, v[82:83]
	v_lshl_add_u64 v[140:141], v[86:87], 0, v[82:83]
	s_waitcnt lgkmcnt(1)
	v_pk_mul_f32 v[84:85], v[130:131], v[88:89] op_sel_hi:[1,0]
	v_pk_mul_f32 v[86:87], v[132:133], v[88:89] op_sel_hi:[1,0]
	v_pk_mul_f32 v[92:93], v[126:127], v[88:89] op_sel_hi:[1,0]
	v_pk_mul_f32 v[90:91], v[128:129], v[88:89] op_sel_hi:[1,0]
	v_pk_mul_f32 v[96:97], v[122:123], v[88:89] op_sel_hi:[1,0]
	v_pk_mul_f32 v[94:95], v[124:125], v[88:89] op_sel_hi:[1,0]
	v_pk_mul_f32 v[100:101], v[118:119], v[88:89] op_sel_hi:[1,0]
	v_pk_mul_f32 v[98:99], v[120:121], v[88:89] op_sel_hi:[1,0]
	v_mov_b32_e32 v88, v89
	s_waitcnt lgkmcnt(0)
	v_pk_mul_f32 v[116:117], v[174:175], v[134:135] op_sel_hi:[1,0]
	v_pk_mul_f32 v[118:119], v[176:177], v[134:135] op_sel_hi:[1,0]
	v_pk_mul_f32 v[120:121], v[170:171], v[134:135] op_sel_hi:[1,0]
	v_pk_mul_f32 v[122:123], v[172:173], v[134:135] op_sel_hi:[1,0]
	v_pk_mul_f32 v[104:105], v[190:191], v[88:89] op_sel_hi:[1,0]
	v_pk_mul_f32 v[102:103], v[192:193], v[88:89] op_sel_hi:[1,0]
	v_pk_mul_f32 v[108:109], v[186:187], v[88:89] op_sel_hi:[1,0]
	v_pk_mul_f32 v[106:107], v[188:189], v[88:89] op_sel_hi:[1,0]
	v_pk_mul_f32 v[112:113], v[182:183], v[88:89] op_sel_hi:[1,0]
	v_pk_mul_f32 v[110:111], v[184:185], v[88:89] op_sel_hi:[1,0]
	v_pk_mul_f32 v[126:127], v[178:179], v[88:89] op_sel_hi:[1,0]
	v_pk_mul_f32 v[114:115], v[180:181], v[88:89] op_sel_hi:[1,0]
	v_pk_mul_f32 v[124:125], v[166:167], v[134:135] op_sel_hi:[1,0]
	s_waitcnt vmcnt(3)
	v_pk_mul_f32 v[86:87], v[14:15], v[86:87]
	v_pk_mul_f32 v[84:85], v[12:13], v[84:85]
	s_waitcnt vmcnt(2)
	v_pk_mul_f32 v[90:91], v[10:11], v[90:91]
	v_pk_mul_f32 v[88:89], v[8:9], v[92:93]
	s_waitcnt vmcnt(1)
	v_pk_mul_f32 v[94:95], v[6:7], v[94:95]
	v_pk_mul_f32 v[92:93], v[4:5], v[96:97]
	s_waitcnt vmcnt(0)
	v_pk_mul_f32 v[98:99], v[2:3], v[98:99]
	v_pk_mul_f32 v[96:97], v[0:1], v[100:101]
	v_pk_mul_f32 v[102:103], v[14:15], v[102:103]
	v_pk_mul_f32 v[100:101], v[12:13], v[104:105]
	v_pk_mul_f32 v[106:107], v[10:11], v[106:107]
	v_pk_mul_f32 v[104:105], v[8:9], v[108:109]
	v_pk_mul_f32 v[110:111], v[6:7], v[110:111]
	v_pk_mul_f32 v[108:109], v[4:5], v[112:113]
	v_pk_mul_f32 v[114:115], v[2:3], v[114:115]
	v_pk_mul_f32 v[112:113], v[0:1], v[126:127]
	v_pk_mul_f32 v[118:119], v[14:15], v[118:119]
	v_pk_mul_f32 v[116:117], v[12:13], v[116:117]
	v_pk_mul_f32 v[122:123], v[10:11], v[122:123]
	v_pk_mul_f32 v[120:121], v[8:9], v[120:121]
	v_mov_b32_e32 v204, v84
	v_mov_b32_e32 v205, v85
	v_mov_b32_e32 v206, v86
	v_mov_b32_e32 v207, v87
	v_cndmask_b32_e64 v220, v88, v204, s[98:99]
	v_cndmask_b32_e64 v221, v89, v205, s[98:99]
	v_cndmask_b32_e64 v222, v90, v206, s[98:99]
	v_cndmask_b32_e64 v223, v91, v207, s[98:99]
	v_mov_b32_dpp v220, v220 quad_perm:[1,0,3,2] row_mask:0xf bank_mask:0xf
	v_mov_b32_dpp v221, v221 quad_perm:[1,0,3,2] row_mask:0xf bank_mask:0xf
	v_mov_b32_dpp v222, v222 quad_perm:[1,0,3,2] row_mask:0xf bank_mask:0xf
	v_mov_b32_dpp v223, v223 quad_perm:[1,0,3,2] row_mask:0xf bank_mask:0xf
	v_lshl_add_u64 v[224:225], v[136:137], 0, v[240:241]
	v_lshl_add_u64 v[226:227], v[136:137], 0, v[242:243]
	v_cndmask_b32_e64 v204, v204, v220, s[98:99]
	v_cndmask_b32_e64 v205, v205, v221, s[98:99]
	v_cndmask_b32_e64 v206, v206, v222, s[98:99]
	v_cndmask_b32_e64 v207, v207, v223, s[98:99]
	v_cndmask_b32_e64 v88, v220, v88, s[98:99]
	v_cndmask_b32_e64 v89, v221, v89, s[98:99]
	v_cndmask_b32_e64 v90, v222, v90, s[98:99]
	v_cndmask_b32_e64 v91, v223, v91, s[98:99]
	global_store_dwordx4 v[224:225], v[204:207], off
	global_store_dwordx4 v[226:227], v[88:91], off
	s_nop 1
	v_mov_b32_e32 v208, v92
	v_mov_b32_e32 v209, v93
	v_mov_b32_e32 v210, v94
	v_mov_b32_e32 v211, v95
	v_cndmask_b32_e64 v220, v96, v208, s[98:99]
	v_cndmask_b32_e64 v221, v97, v209, s[98:99]
	v_cndmask_b32_e64 v222, v98, v210, s[98:99]
	v_cndmask_b32_e64 v223, v99, v211, s[98:99]
	v_mov_b32_dpp v220, v220 quad_perm:[1,0,3,2] row_mask:0xf bank_mask:0xf
	v_mov_b32_dpp v221, v221 quad_perm:[1,0,3,2] row_mask:0xf bank_mask:0xf
	v_mov_b32_dpp v222, v222 quad_perm:[1,0,3,2] row_mask:0xf bank_mask:0xf
	v_mov_b32_dpp v223, v223 quad_perm:[1,0,3,2] row_mask:0xf bank_mask:0xf
	v_lshl_add_u64 v[224:225], v[136:137], 0, v[240:241]
	v_lshl_add_u64 v[226:227], v[136:137], 0, v[242:243]
	v_cndmask_b32_e64 v208, v208, v220, s[98:99]
	v_cndmask_b32_e64 v209, v209, v221, s[98:99]
	v_cndmask_b32_e64 v210, v210, v222, s[98:99]
	v_cndmask_b32_e64 v211, v211, v223, s[98:99]
	v_cndmask_b32_e64 v96, v220, v96, s[98:99]
	v_cndmask_b32_e64 v97, v221, v97, s[98:99]
	v_cndmask_b32_e64 v98, v222, v98, s[98:99]
	v_cndmask_b32_e64 v99, v223, v99, s[98:99]
	global_store_dwordx4 v[224:225], v[208:211], off offset:512
	global_store_dwordx4 v[226:227], v[96:99], off offset:512
	s_nop 1
	v_mov_b32_e32 v212, v100
	v_mov_b32_e32 v213, v101
	v_mov_b32_e32 v214, v102
	v_mov_b32_e32 v215, v103
	v_cndmask_b32_e64 v220, v104, v212, s[98:99]
	v_cndmask_b32_e64 v221, v105, v213, s[98:99]
	v_cndmask_b32_e64 v222, v106, v214, s[98:99]
	v_cndmask_b32_e64 v223, v107, v215, s[98:99]
	v_mov_b32_dpp v220, v220 quad_perm:[1,0,3,2] row_mask:0xf bank_mask:0xf
	v_mov_b32_dpp v221, v221 quad_perm:[1,0,3,2] row_mask:0xf bank_mask:0xf
	v_mov_b32_dpp v222, v222 quad_perm:[1,0,3,2] row_mask:0xf bank_mask:0xf
	v_mov_b32_dpp v223, v223 quad_perm:[1,0,3,2] row_mask:0xf bank_mask:0xf
	v_lshl_add_u64 v[224:225], v[138:139], 0, v[240:241]
	v_lshl_add_u64 v[226:227], v[138:139], 0, v[242:243]
	v_cndmask_b32_e64 v212, v212, v220, s[98:99]
	v_cndmask_b32_e64 v213, v213, v221, s[98:99]
	v_cndmask_b32_e64 v214, v214, v222, s[98:99]
	v_cndmask_b32_e64 v215, v215, v223, s[98:99]
	v_cndmask_b32_e64 v104, v220, v104, s[98:99]
	v_cndmask_b32_e64 v105, v221, v105, s[98:99]
	v_cndmask_b32_e64 v106, v222, v106, s[98:99]
	v_cndmask_b32_e64 v107, v223, v107, s[98:99]
	global_store_dwordx4 v[224:225], v[212:215], off
	global_store_dwordx4 v[226:227], v[104:107], off
	s_nop 1
	v_mov_b32_e32 v216, v108
	v_mov_b32_e32 v217, v109
	v_mov_b32_e32 v218, v110
	v_mov_b32_e32 v219, v111
	v_cndmask_b32_e64 v220, v112, v216, s[98:99]
	v_cndmask_b32_e64 v221, v113, v217, s[98:99]
	v_cndmask_b32_e64 v222, v114, v218, s[98:99]
	v_cndmask_b32_e64 v223, v115, v219, s[98:99]
	v_mov_b32_dpp v220, v220 quad_perm:[1,0,3,2] row_mask:0xf bank_mask:0xf
	v_mov_b32_dpp v221, v221 quad_perm:[1,0,3,2] row_mask:0xf bank_mask:0xf
	v_mov_b32_dpp v222, v222 quad_perm:[1,0,3,2] row_mask:0xf bank_mask:0xf
	v_mov_b32_dpp v223, v223 quad_perm:[1,0,3,2] row_mask:0xf bank_mask:0xf
	v_lshl_add_u64 v[224:225], v[138:139], 0, v[240:241]
	v_lshl_add_u64 v[226:227], v[138:139], 0, v[242:243]
	v_cndmask_b32_e64 v216, v216, v220, s[98:99]
	v_cndmask_b32_e64 v217, v217, v221, s[98:99]
	v_cndmask_b32_e64 v218, v218, v222, s[98:99]
	v_cndmask_b32_e64 v219, v219, v223, s[98:99]
	v_cndmask_b32_e64 v112, v220, v112, s[98:99]
	v_cndmask_b32_e64 v113, v221, v113, s[98:99]
	v_cndmask_b32_e64 v114, v222, v114, s[98:99]
	v_cndmask_b32_e64 v115, v223, v115, s[98:99]
	global_store_dwordx4 v[224:225], v[216:219], off offset:512
	global_store_dwordx4 v[226:227], v[112:115], off offset:512
	s_nop 1
	v_mov_b32_e32 v204, v116
	v_mov_b32_e32 v205, v117
	v_mov_b32_e32 v206, v118
	v_mov_b32_e32 v207, v119
	v_cndmask_b32_e64 v220, v120, v204, s[98:99]
	v_cndmask_b32_e64 v221, v121, v205, s[98:99]
	v_cndmask_b32_e64 v222, v122, v206, s[98:99]
	v_cndmask_b32_e64 v223, v123, v207, s[98:99]
	v_mov_b32_dpp v220, v220 quad_perm:[1,0,3,2] row_mask:0xf bank_mask:0xf
	v_mov_b32_dpp v221, v221 quad_perm:[1,0,3,2] row_mask:0xf bank_mask:0xf
	v_mov_b32_dpp v222, v222 quad_perm:[1,0,3,2] row_mask:0xf bank_mask:0xf
	v_mov_b32_dpp v223, v223 quad_perm:[1,0,3,2] row_mask:0xf bank_mask:0xf
	v_lshl_add_u64 v[224:225], v[140:141], 0, v[240:241]
	v_lshl_add_u64 v[226:227], v[140:141], 0, v[242:243]
	v_cndmask_b32_e64 v204, v204, v220, s[98:99]
	v_cndmask_b32_e64 v205, v205, v221, s[98:99]
	v_cndmask_b32_e64 v206, v206, v222, s[98:99]
	v_cndmask_b32_e64 v207, v207, v223, s[98:99]
	v_cndmask_b32_e64 v120, v220, v120, s[98:99]
	v_cndmask_b32_e64 v121, v221, v121, s[98:99]
	v_cndmask_b32_e64 v122, v222, v122, s[98:99]
	v_cndmask_b32_e64 v123, v223, v123, s[98:99]
	global_store_dwordx4 v[224:225], v[204:207], off
	global_store_dwordx4 v[226:227], v[120:123], off
	s_nop 1
	v_pk_mul_f32 v[84:85], v[168:169], v[134:135] op_sel_hi:[1,0]
	v_add_u32_e32 v88, 48, v76
	v_pk_mul_f32 v[86:87], v[6:7], v[84:85]
	v_pk_mul_f32 v[84:85], v[4:5], v[124:125]
	v_mov_b32_e32 v208, v84
	v_mov_b32_e32 v209, v85
	v_mov_b32_e32 v210, v86
	v_mov_b32_e32 v211, v87
	v_ashrrev_i32_e32 v89, 31, v88
	v_mov_b32_e32 v90, v135
	v_pk_mul_f32 v[84:85], v[162:163], v[134:135] op_sel_hi:[1,0]
	v_pk_mul_f32 v[86:87], v[164:165], v[134:135] op_sel_hi:[1,0]
	v_pk_mul_f32 v[84:85], v[0:1], v[84:85]
	v_pk_mul_f32 v[86:87], v[2:3], v[86:87]
	v_lshlrev_b64 v[88:89], 12, v[88:89]
	v_cndmask_b32_e64 v220, v84, v208, s[98:99]
	v_cndmask_b32_e64 v221, v85, v209, s[98:99]
	v_cndmask_b32_e64 v222, v86, v210, s[98:99]
	v_cndmask_b32_e64 v223, v87, v211, s[98:99]
	v_mov_b32_dpp v220, v220 quad_perm:[1,0,3,2] row_mask:0xf bank_mask:0xf
	v_mov_b32_dpp v221, v221 quad_perm:[1,0,3,2] row_mask:0xf bank_mask:0xf
	v_mov_b32_dpp v222, v222 quad_perm:[1,0,3,2] row_mask:0xf bank_mask:0xf
	v_mov_b32_dpp v223, v223 quad_perm:[1,0,3,2] row_mask:0xf bank_mask:0xf
	v_lshl_add_u64 v[224:225], v[140:141], 0, v[240:241]
	v_lshl_add_u64 v[226:227], v[140:141], 0, v[242:243]
	v_cndmask_b32_e64 v208, v208, v220, s[98:99]
	v_cndmask_b32_e64 v209, v209, v221, s[98:99]
	v_cndmask_b32_e64 v210, v210, v222, s[98:99]
	v_cndmask_b32_e64 v211, v211, v223, s[98:99]
	v_cndmask_b32_e64 v84, v220, v84, s[98:99]
	v_cndmask_b32_e64 v85, v221, v85, s[98:99]
	v_cndmask_b32_e64 v86, v222, v86, s[98:99]
	v_cndmask_b32_e64 v87, v223, v87, s[98:99]
	global_store_dwordx4 v[224:225], v[208:211], off offset:512
	global_store_dwordx4 v[226:227], v[84:87], off offset:512
	s_nop 1
	v_lshl_add_u64 v[88:89], s[78:79], 0, v[88:89]
	v_lshl_add_u64 v[88:89], v[88:89], 0, v[82:83]
	v_pk_mul_f32 v[84:85], v[158:159], v[90:91] op_sel_hi:[1,0]
	v_pk_mul_f32 v[86:87], v[160:161], v[90:91] op_sel_hi:[1,0]
	v_pk_mul_f32 v[84:85], v[12:13], v[84:85]
	v_pk_mul_f32 v[86:87], v[14:15], v[86:87]
	v_mov_b32_e32 v212, v84
	v_mov_b32_e32 v213, v85
	v_mov_b32_e32 v214, v86
	v_mov_b32_e32 v215, v87
	s_nop 1
	v_pk_mul_f32 v[84:85], v[154:155], v[90:91] op_sel_hi:[1,0]
	v_pk_mul_f32 v[86:87], v[156:157], v[90:91] op_sel_hi:[1,0]
	v_pk_mul_f32 v[84:85], v[8:9], v[84:85]
	v_pk_mul_f32 v[86:87], v[10:11], v[86:87]
	v_cndmask_b32_e64 v220, v84, v212, s[98:99]
	v_cndmask_b32_e64 v221, v85, v213, s[98:99]
	v_cndmask_b32_e64 v222, v86, v214, s[98:99]
	v_cndmask_b32_e64 v223, v87, v215, s[98:99]
	v_mov_b32_dpp v220, v220 quad_perm:[1,0,3,2] row_mask:0xf bank_mask:0xf
	v_mov_b32_dpp v221, v221 quad_perm:[1,0,3,2] row_mask:0xf bank_mask:0xf
	v_mov_b32_dpp v222, v222 quad_perm:[1,0,3,2] row_mask:0xf bank_mask:0xf
	v_mov_b32_dpp v223, v223 quad_perm:[1,0,3,2] row_mask:0xf bank_mask:0xf
	v_lshl_add_u64 v[224:225], v[88:89], 0, v[240:241]
	v_lshl_add_u64 v[226:227], v[88:89], 0, v[242:243]
	v_cndmask_b32_e64 v212, v212, v220, s[98:99]
	v_cndmask_b32_e64 v213, v213, v221, s[98:99]
	v_cndmask_b32_e64 v214, v214, v222, s[98:99]
	v_cndmask_b32_e64 v215, v215, v223, s[98:99]
	v_cndmask_b32_e64 v84, v220, v84, s[98:99]
	v_cndmask_b32_e64 v85, v221, v85, s[98:99]
	v_cndmask_b32_e64 v86, v222, v86, s[98:99]
	v_cndmask_b32_e64 v87, v223, v87, s[98:99]
	global_store_dwordx4 v[224:225], v[212:215], off
	global_store_dwordx4 v[226:227], v[84:87], off
	s_nop 1
	s_nop 1
	v_pk_mul_f32 v[84:85], v[150:151], v[90:91] op_sel_hi:[1,0]
	v_pk_mul_f32 v[86:87], v[152:153], v[90:91] op_sel_hi:[1,0]
	v_pk_mul_f32 v[84:85], v[4:5], v[84:85]
	v_pk_mul_f32 v[86:87], v[6:7], v[86:87]
	v_mov_b32_e32 v216, v84
	v_mov_b32_e32 v217, v85
	v_mov_b32_e32 v218, v86
	v_mov_b32_e32 v219, v87
	s_nop 1
	v_pk_mul_f32 v[84:85], v[146:147], v[90:91] op_sel_hi:[1,0]
	v_pk_mul_f32 v[86:87], v[148:149], v[90:91] op_sel_hi:[1,0]
	ds_read2_b32 v[90:91], v142 offset0:128 offset1:144
	v_pk_mul_f32 v[86:87], v[2:3], v[86:87]
	v_pk_mul_f32 v[84:85], v[0:1], v[84:85]
	v_cndmask_b32_e64 v220, v84, v216, s[98:99]
	v_cndmask_b32_e64 v221, v85, v217, s[98:99]
	v_cndmask_b32_e64 v222, v86, v218, s[98:99]
	v_cndmask_b32_e64 v223, v87, v219, s[98:99]
	v_mov_b32_dpp v220, v220 quad_perm:[1,0,3,2] row_mask:0xf bank_mask:0xf
	v_mov_b32_dpp v221, v221 quad_perm:[1,0,3,2] row_mask:0xf bank_mask:0xf
	v_mov_b32_dpp v222, v222 quad_perm:[1,0,3,2] row_mask:0xf bank_mask:0xf
	v_mov_b32_dpp v223, v223 quad_perm:[1,0,3,2] row_mask:0xf bank_mask:0xf
	v_lshl_add_u64 v[224:225], v[88:89], 0, v[240:241]
	v_lshl_add_u64 v[226:227], v[88:89], 0, v[242:243]
	v_cndmask_b32_e64 v216, v216, v220, s[98:99]
	v_cndmask_b32_e64 v217, v217, v221, s[98:99]
	v_cndmask_b32_e64 v218, v218, v222, s[98:99]
	v_cndmask_b32_e64 v219, v219, v223, s[98:99]
	v_cndmask_b32_e64 v84, v220, v84, s[98:99]
	v_cndmask_b32_e64 v85, v221, v85, s[98:99]
	v_cndmask_b32_e64 v86, v222, v86, s[98:99]
	v_cndmask_b32_e64 v87, v223, v87, s[98:99]
	global_store_dwordx4 v[224:225], v[216:219], off offset:512
	global_store_dwordx4 v[226:227], v[84:87], off offset:512
	s_nop 1
	s_waitcnt lgkmcnt(0)
	v_pk_mul_f32 v[50:51], v[50:51], v[90:91] op_sel_hi:[1,0]
	v_add_u32_e32 v84, 0x80, v76
	v_ashrrev_i32_e32 v85, 31, v84
	v_lshlrev_b64 v[84:85], 12, v[84:85]
	v_lshl_add_u64 v[84:85], s[78:79], 0, v[84:85]
	v_pk_mul_f32 v[52:53], v[52:53], v[90:91] op_sel_hi:[1,0]
	v_lshl_add_u64 v[84:85], v[84:85], 0, v[82:83]
	v_pk_mul_f32 v[52:53], v[2:3], v[52:53]
	v_pk_mul_f32 v[50:51], v[0:1], v[50:51]
	v_mov_b32_e32 v204, v50
	v_mov_b32_e32 v205, v51
	v_mov_b32_e32 v206, v52
	v_mov_b32_e32 v207, v53
	v_pk_mul_f32 v[62:63], v[62:63], v[90:91] op_sel_hi:[1,0]
	v_pk_mul_f32 v[64:65], v[64:65], v[90:91] op_sel_hi:[1,0]
	v_add_u32_e32 v50, 0x90, v76
	v_ashrrev_i32_e32 v51, 31, v50
	v_mov_b32_e32 v52, v91
	v_lshlrev_b64 v[50:51], 12, v[50:51]
	v_lshl_add_u64 v[50:51], s[78:79], 0, v[50:51]
	v_pk_mul_f32 v[38:39], v[38:39], v[52:53] op_sel_hi:[1,0]
	v_pk_mul_f32 v[40:41], v[40:41], v[52:53] op_sel_hi:[1,0]
	v_lshl_add_u64 v[50:51], v[50:51], 0, v[82:83]
	v_pk_mul_f32 v[40:41], v[6:7], v[40:41]
	v_pk_mul_f32 v[38:39], v[4:5], v[38:39]
	v_mov_b32_e32 v208, v38
	v_mov_b32_e32 v209, v39
	v_mov_b32_e32 v210, v40
	v_mov_b32_e32 v211, v41
	v_pk_mul_f32 v[34:35], v[34:35], v[52:53] op_sel_hi:[1,0]
	v_pk_mul_f32 v[36:37], v[36:37], v[52:53] op_sel_hi:[1,0]
	ds_read2_b32 v[38:39], v142 offset0:160 offset1:176
	v_pk_mul_f32 v[36:37], v[2:3], v[36:37]
	v_pk_mul_f32 v[34:35], v[0:1], v[34:35]
	v_cndmask_b32_e64 v220, v34, v208, s[98:99]
	v_cndmask_b32_e64 v221, v35, v209, s[98:99]
	v_cndmask_b32_e64 v222, v36, v210, s[98:99]
	v_cndmask_b32_e64 v223, v37, v211, s[98:99]
	v_mov_b32_dpp v220, v220 quad_perm:[1,0,3,2] row_mask:0xf bank_mask:0xf
	v_mov_b32_dpp v221, v221 quad_perm:[1,0,3,2] row_mask:0xf bank_mask:0xf
	v_mov_b32_dpp v222, v222 quad_perm:[1,0,3,2] row_mask:0xf bank_mask:0xf
	v_mov_b32_dpp v223, v223 quad_perm:[1,0,3,2] row_mask:0xf bank_mask:0xf
	v_lshl_add_u64 v[224:225], v[50:51], 0, v[240:241]
	v_lshl_add_u64 v[226:227], v[50:51], 0, v[242:243]
	v_cndmask_b32_e64 v208, v208, v220, s[98:99]
	v_cndmask_b32_e64 v209, v209, v221, s[98:99]
	v_cndmask_b32_e64 v210, v210, v222, s[98:99]
	v_cndmask_b32_e64 v211, v211, v223, s[98:99]
	v_cndmask_b32_e64 v34, v220, v34, s[98:99]
	v_cndmask_b32_e64 v35, v221, v35, s[98:99]
	v_cndmask_b32_e64 v36, v222, v36, s[98:99]
	v_cndmask_b32_e64 v37, v223, v37, s[98:99]
	global_store_dwordx4 v[224:225], v[208:211], off offset:512
	global_store_dwordx4 v[226:227], v[34:37], off offset:512
	s_nop 1
	v_pk_mul_f32 v[46:47], v[46:47], v[52:53] op_sel_hi:[1,0]
	s_waitcnt lgkmcnt(0)
	v_pk_mul_f32 v[18:19], v[18:19], v[38:39] op_sel_hi:[1,0]
	v_add_u32_e32 v34, 0xa0, v76
	v_ashrrev_i32_e32 v35, 31, v34
	v_lshlrev_b64 v[34:35], 12, v[34:35]
	v_lshl_add_u64 v[34:35], s[78:79], 0, v[34:35]
	v_pk_mul_f32 v[20:21], v[20:21], v[38:39] op_sel_hi:[1,0]
	v_lshl_add_u64 v[34:35], v[34:35], 0, v[82:83]
	v_pk_mul_f32 v[20:21], v[2:3], v[20:21]
	v_pk_mul_f32 v[18:19], v[0:1], v[18:19]
	v_mov_b32_e32 v212, v18
	v_mov_b32_e32 v213, v19
	v_mov_b32_e32 v214, v20
	v_mov_b32_e32 v215, v21
	v_pk_mul_f32 v[22:23], v[22:23], v[38:39] op_sel_hi:[1,0]
	v_pk_mul_f32 v[24:25], v[24:25], v[38:39] op_sel_hi:[1,0]
	v_add_u32_e32 v18, 0xb0, v76
	v_ashrrev_i32_e32 v19, 31, v18
	v_pk_mul_f32 v[24:25], v[6:7], v[24:25]
	v_pk_mul_f32 v[22:23], v[4:5], v[22:23]
	v_mov_b32_e32 v20, v39
	v_lshlrev_b64 v[18:19], 12, v[18:19]
	v_pk_mul_f32 v[48:49], v[48:49], v[52:53] op_sel_hi:[1,0]
	v_pk_mul_f32 v[30:31], v[30:31], v[38:39] op_sel_hi:[1,0]
	v_pk_mul_f32 v[32:33], v[32:33], v[38:39] op_sel_hi:[1,0]
	v_cndmask_b32_e64 v220, v212, v22, s[98:99]
	v_cndmask_b32_e64 v221, v213, v23, s[98:99]
	v_cndmask_b32_e64 v222, v214, v24, s[98:99]
	v_cndmask_b32_e64 v223, v215, v25, s[98:99]
	v_mov_b32_dpp v220, v220 quad_perm:[1,0,3,2] row_mask:0xf bank_mask:0xf
	v_mov_b32_dpp v221, v221 quad_perm:[1,0,3,2] row_mask:0xf bank_mask:0xf
	v_mov_b32_dpp v222, v222 quad_perm:[1,0,3,2] row_mask:0xf bank_mask:0xf
	v_mov_b32_dpp v223, v223 quad_perm:[1,0,3,2] row_mask:0xf bank_mask:0xf
	v_lshl_add_u64 v[224:225], v[34:35], 0, v[240:241]
	v_lshl_add_u64 v[226:227], v[34:35], 0, v[242:243]
	v_cndmask_b32_e64 v22, v22, v220, s[98:99]
	v_cndmask_b32_e64 v23, v23, v221, s[98:99]
	v_cndmask_b32_e64 v24, v24, v222, s[98:99]
	v_cndmask_b32_e64 v25, v25, v223, s[98:99]
	v_cndmask_b32_e64 v212, v220, v212, s[98:99]
	v_cndmask_b32_e64 v213, v221, v213, s[98:99]
	v_cndmask_b32_e64 v214, v222, v214, s[98:99]
	v_cndmask_b32_e64 v215, v223, v215, s[98:99]
	global_store_dwordx4 v[224:225], v[22:25], off offset:512
	global_store_dwordx4 v[226:227], v[212:215], off offset:512
	s_nop 1
	v_lshl_add_u64 v[18:19], s[78:79], 0, v[18:19]
	v_pk_mul_f32 v[64:65], v[14:15], v[64:65]
	v_pk_mul_f32 v[22:23], v[78:79], v[20:21] op_sel_hi:[1,0]
	v_pk_mul_f32 v[24:25], v[80:81], v[20:21] op_sel_hi:[1,0]
	v_pk_mul_f32 v[62:63], v[12:13], v[62:63]
	v_pk_mul_f32 v[48:49], v[14:15], v[48:49]
	v_pk_mul_f32 v[46:47], v[12:13], v[46:47]
	v_pk_mul_f32 v[32:33], v[14:15], v[32:33]
	v_pk_mul_f32 v[30:31], v[12:13], v[30:31]
	v_pk_mul_f32 v[14:15], v[14:15], v[24:25]
	v_pk_mul_f32 v[12:13], v[12:13], v[22:23]
	v_lshl_add_u64 v[18:19], v[18:19], 0, v[82:83]
	v_pk_mul_f32 v[58:59], v[58:59], v[90:91] op_sel_hi:[1,0]
	v_pk_mul_f32 v[60:61], v[60:61], v[90:91] op_sel_hi:[1,0]
	v_pk_mul_f32 v[42:43], v[42:43], v[52:53] op_sel_hi:[1,0]
	v_pk_mul_f32 v[44:45], v[44:45], v[52:53] op_sel_hi:[1,0]
	v_pk_mul_f32 v[26:27], v[26:27], v[38:39] op_sel_hi:[1,0]
	v_pk_mul_f32 v[28:29], v[28:29], v[38:39] op_sel_hi:[1,0]
	v_mov_b32_e32 v216, v12
	v_mov_b32_e32 v217, v13
	v_mov_b32_e32 v218, v14
	v_mov_b32_e32 v219, v15
	v_pk_mul_f32 v[60:61], v[10:11], v[60:61]
	v_pk_mul_f32 v[58:59], v[8:9], v[58:59]
	v_pk_mul_f32 v[12:13], v[74:75], v[20:21] op_sel_hi:[1,0]
	v_pk_mul_f32 v[14:15], v[16:17], v[20:21] op_sel_hi:[1,0]
	v_pk_mul_f32 v[44:45], v[10:11], v[44:45]
	v_pk_mul_f32 v[42:43], v[8:9], v[42:43]
	v_pk_mul_f32 v[28:29], v[10:11], v[28:29]
	v_pk_mul_f32 v[26:27], v[8:9], v[26:27]
	v_pk_mul_f32 v[10:11], v[10:11], v[14:15]
	v_pk_mul_f32 v[8:9], v[8:9], v[12:13]
	v_pk_mul_f32 v[54:55], v[54:55], v[90:91] op_sel_hi:[1,0]
	v_pk_mul_f32 v[56:57], v[56:57], v[90:91] op_sel_hi:[1,0]
	v_cndmask_b32_e64 v220, v8, v216, s[98:99]
	v_cndmask_b32_e64 v221, v9, v217, s[98:99]
	v_cndmask_b32_e64 v222, v10, v218, s[98:99]
	v_cndmask_b32_e64 v223, v11, v219, s[98:99]
	v_mov_b32_dpp v220, v220 quad_perm:[1,0,3,2] row_mask:0xf bank_mask:0xf
	v_mov_b32_dpp v221, v221 quad_perm:[1,0,3,2] row_mask:0xf bank_mask:0xf
	v_mov_b32_dpp v222, v222 quad_perm:[1,0,3,2] row_mask:0xf bank_mask:0xf
	v_mov_b32_dpp v223, v223 quad_perm:[1,0,3,2] row_mask:0xf bank_mask:0xf
	v_lshl_add_u64 v[224:225], v[18:19], 0, v[240:241]
	v_lshl_add_u64 v[226:227], v[18:19], 0, v[242:243]
	v_cndmask_b32_e64 v216, v216, v220, s[98:99]
	v_cndmask_b32_e64 v217, v217, v221, s[98:99]
	v_cndmask_b32_e64 v218, v218, v222, s[98:99]
	v_cndmask_b32_e64 v219, v219, v223, s[98:99]
	v_cndmask_b32_e64 v8, v220, v8, s[98:99]
	v_cndmask_b32_e64 v9, v221, v9, s[98:99]
	v_cndmask_b32_e64 v10, v222, v10, s[98:99]
	v_cndmask_b32_e64 v11, v223, v11, s[98:99]
	global_store_dwordx4 v[224:225], v[216:219], off
	global_store_dwordx4 v[226:227], v[8:11], off
	s_nop 1
	v_pk_mul_f32 v[56:57], v[6:7], v[56:57]
	v_pk_mul_f32 v[54:55], v[4:5], v[54:55]
	v_pk_mul_f32 v[8:9], v[70:71], v[20:21] op_sel_hi:[1,0]
	v_pk_mul_f32 v[10:11], v[72:73], v[20:21] op_sel_hi:[1,0]
	v_pk_mul_f32 v[4:5], v[4:5], v[8:9]
	v_pk_mul_f32 v[6:7], v[6:7], v[10:11]
	v_mov_b32_e32 v208, v4
	v_mov_b32_e32 v209, v5
	v_mov_b32_e32 v210, v6
	v_mov_b32_e32 v211, v7
	v_mov_b32_e32 v212, v62
	v_mov_b32_e32 v213, v63
	v_mov_b32_e32 v214, v64
	v_mov_b32_e32 v215, v65
	v_cndmask_b32_e64 v220, v58, v212, s[98:99]
	v_cndmask_b32_e64 v221, v59, v213, s[98:99]
	v_cndmask_b32_e64 v222, v60, v214, s[98:99]
	v_cndmask_b32_e64 v223, v61, v215, s[98:99]
	v_mov_b32_dpp v220, v220 quad_perm:[1,0,3,2] row_mask:0xf bank_mask:0xf
	v_mov_b32_dpp v221, v221 quad_perm:[1,0,3,2] row_mask:0xf bank_mask:0xf
	v_mov_b32_dpp v222, v222 quad_perm:[1,0,3,2] row_mask:0xf bank_mask:0xf
	v_mov_b32_dpp v223, v223 quad_perm:[1,0,3,2] row_mask:0xf bank_mask:0xf
	v_lshl_add_u64 v[224:225], v[84:85], 0, v[240:241]
	v_lshl_add_u64 v[226:227], v[84:85], 0, v[242:243]
	v_cndmask_b32_e64 v212, v212, v220, s[98:99]
	v_cndmask_b32_e64 v213, v213, v221, s[98:99]
	v_cndmask_b32_e64 v214, v214, v222, s[98:99]
	v_cndmask_b32_e64 v215, v215, v223, s[98:99]
	v_cndmask_b32_e64 v58, v220, v58, s[98:99]
	v_cndmask_b32_e64 v59, v221, v59, s[98:99]
	v_cndmask_b32_e64 v60, v222, v60, s[98:99]
	v_cndmask_b32_e64 v61, v223, v61, s[98:99]
	global_store_dwordx4 v[224:225], v[212:215], off
	global_store_dwordx4 v[226:227], v[58:61], off
	s_nop 1
	v_pk_mul_f32 v[4:5], v[66:67], v[20:21] op_sel_hi:[1,0]
	v_pk_mul_f32 v[6:7], v[68:69], v[20:21] op_sel_hi:[1,0]
	v_pk_mul_f32 v[0:1], v[0:1], v[4:5]
	v_pk_mul_f32 v[2:3], v[2:3], v[6:7]
	v_cndmask_b32_e64 v220, v204, v54, s[98:99]
	v_cndmask_b32_e64 v221, v205, v55, s[98:99]
	v_cndmask_b32_e64 v222, v206, v56, s[98:99]
	v_cndmask_b32_e64 v223, v207, v57, s[98:99]
	v_mov_b32_dpp v220, v220 quad_perm:[1,0,3,2] row_mask:0xf bank_mask:0xf
	v_mov_b32_dpp v221, v221 quad_perm:[1,0,3,2] row_mask:0xf bank_mask:0xf
	v_mov_b32_dpp v222, v222 quad_perm:[1,0,3,2] row_mask:0xf bank_mask:0xf
	v_mov_b32_dpp v223, v223 quad_perm:[1,0,3,2] row_mask:0xf bank_mask:0xf
	v_lshl_add_u64 v[224:225], v[84:85], 0, v[240:241]
	v_lshl_add_u64 v[226:227], v[84:85], 0, v[242:243]
	v_cndmask_b32_e64 v54, v54, v220, s[98:99]
	v_cndmask_b32_e64 v55, v55, v221, s[98:99]
	v_cndmask_b32_e64 v56, v56, v222, s[98:99]
	v_cndmask_b32_e64 v57, v57, v223, s[98:99]
	v_cndmask_b32_e64 v204, v220, v204, s[98:99]
	v_cndmask_b32_e64 v205, v221, v205, s[98:99]
	v_cndmask_b32_e64 v206, v222, v206, s[98:99]
	v_cndmask_b32_e64 v207, v223, v207, s[98:99]
	global_store_dwordx4 v[224:225], v[54:57], off offset:512
	global_store_dwordx4 v[226:227], v[204:207], off offset:512
	s_nop 1
	v_mov_b32_e32 v216, v46
	v_mov_b32_e32 v217, v47
	v_mov_b32_e32 v218, v48
	v_mov_b32_e32 v219, v49
	v_cndmask_b32_e64 v220, v42, v216, s[98:99]
	v_cndmask_b32_e64 v221, v43, v217, s[98:99]
	v_cndmask_b32_e64 v222, v44, v218, s[98:99]
	v_cndmask_b32_e64 v223, v45, v219, s[98:99]
	v_mov_b32_dpp v220, v220 quad_perm:[1,0,3,2] row_mask:0xf bank_mask:0xf
	v_mov_b32_dpp v221, v221 quad_perm:[1,0,3,2] row_mask:0xf bank_mask:0xf
	v_mov_b32_dpp v222, v222 quad_perm:[1,0,3,2] row_mask:0xf bank_mask:0xf
	v_mov_b32_dpp v223, v223 quad_perm:[1,0,3,2] row_mask:0xf bank_mask:0xf
	v_lshl_add_u64 v[224:225], v[50:51], 0, v[240:241]
	v_lshl_add_u64 v[226:227], v[50:51], 0, v[242:243]
	v_cndmask_b32_e64 v216, v216, v220, s[98:99]
	v_cndmask_b32_e64 v217, v217, v221, s[98:99]
	v_cndmask_b32_e64 v218, v218, v222, s[98:99]
	v_cndmask_b32_e64 v219, v219, v223, s[98:99]
	v_cndmask_b32_e64 v42, v220, v42, s[98:99]
	v_cndmask_b32_e64 v43, v221, v43, s[98:99]
	v_cndmask_b32_e64 v44, v222, v44, s[98:99]
	v_cndmask_b32_e64 v45, v223, v45, s[98:99]
	global_store_dwordx4 v[224:225], v[216:219], off
	global_store_dwordx4 v[226:227], v[42:45], off
	s_nop 1
	v_mov_b32_e32 v212, v30
	v_mov_b32_e32 v213, v31
	v_mov_b32_e32 v214, v32
	v_mov_b32_e32 v215, v33
	v_cndmask_b32_e64 v220, v26, v212, s[98:99]
	v_cndmask_b32_e64 v221, v27, v213, s[98:99]
	v_cndmask_b32_e64 v222, v28, v214, s[98:99]
	v_cndmask_b32_e64 v223, v29, v215, s[98:99]
	v_mov_b32_dpp v220, v220 quad_perm:[1,0,3,2] row_mask:0xf bank_mask:0xf
	v_mov_b32_dpp v221, v221 quad_perm:[1,0,3,2] row_mask:0xf bank_mask:0xf
	v_mov_b32_dpp v222, v222 quad_perm:[1,0,3,2] row_mask:0xf bank_mask:0xf
	v_mov_b32_dpp v223, v223 quad_perm:[1,0,3,2] row_mask:0xf bank_mask:0xf
	v_lshl_add_u64 v[224:225], v[34:35], 0, v[240:241]
	v_lshl_add_u64 v[226:227], v[34:35], 0, v[242:243]
	v_cndmask_b32_e64 v212, v212, v220, s[98:99]
	v_cndmask_b32_e64 v213, v213, v221, s[98:99]
	v_cndmask_b32_e64 v214, v214, v222, s[98:99]
	v_cndmask_b32_e64 v215, v215, v223, s[98:99]
	v_cndmask_b32_e64 v26, v220, v26, s[98:99]
	v_cndmask_b32_e64 v27, v221, v27, s[98:99]
	v_cndmask_b32_e64 v28, v222, v28, s[98:99]
	v_cndmask_b32_e64 v29, v223, v29, s[98:99]
	global_store_dwordx4 v[224:225], v[212:215], off
	global_store_dwordx4 v[226:227], v[26:29], off
	s_nop 1
	v_cndmask_b32_e64 v220, v0, v208, s[98:99]
	v_cndmask_b32_e64 v221, v1, v209, s[98:99]
	v_cndmask_b32_e64 v222, v2, v210, s[98:99]
	v_cndmask_b32_e64 v223, v3, v211, s[98:99]
	v_mov_b32_dpp v220, v220 quad_perm:[1,0,3,2] row_mask:0xf bank_mask:0xf
	v_mov_b32_dpp v221, v221 quad_perm:[1,0,3,2] row_mask:0xf bank_mask:0xf
	v_mov_b32_dpp v222, v222 quad_perm:[1,0,3,2] row_mask:0xf bank_mask:0xf
	v_mov_b32_dpp v223, v223 quad_perm:[1,0,3,2] row_mask:0xf bank_mask:0xf
	v_lshl_add_u64 v[224:225], v[18:19], 0, v[240:241]
	v_lshl_add_u64 v[226:227], v[18:19], 0, v[242:243]
	v_cndmask_b32_e64 v208, v208, v220, s[98:99]
	v_cndmask_b32_e64 v209, v209, v221, s[98:99]
	v_cndmask_b32_e64 v210, v210, v222, s[98:99]
	v_cndmask_b32_e64 v211, v211, v223, s[98:99]
	v_cndmask_b32_e64 v0, v220, v0, s[98:99]
	v_cndmask_b32_e64 v1, v221, v1, s[98:99]
	v_cndmask_b32_e64 v2, v222, v2, s[98:99]
	v_cndmask_b32_e64 v3, v223, v3, s[98:99]
	global_store_dwordx4 v[224:225], v[208:211], off offset:512
	global_store_dwordx4 v[226:227], v[0:3], off offset:512
	s_nop 1

	.amdhsa_kernel _Z6mk_fwd4Args
		.amdhsa_group_segment_fixed_size 0
		.amdhsa_private_segment_fixed_size 0
		.amdhsa_kernarg_size 416
		.amdhsa_user_sgpr_count 2
		.amdhsa_user_sgpr_dispatch_ptr 0
		.amdhsa_user_sgpr_queue_ptr 0
		.amdhsa_user_sgpr_kernarg_segment_ptr 1
		.amdhsa_user_sgpr_dispatch_id 0
		.amdhsa_user_sgpr_kernarg_preload_length 0
		.amdhsa_user_sgpr_kernarg_preload_offset 0
		.amdhsa_user_sgpr_private_segment_size 0
		.amdhsa_uses_dynamic_stack 0
		.amdhsa_enable_private_segment 0
		.amdhsa_system_sgpr_workgroup_id_x 1
		.amdhsa_system_sgpr_workgroup_id_y 0
		.amdhsa_system_sgpr_workgroup_id_z 0
		.amdhsa_system_sgpr_workgroup_info 0
		.amdhsa_system_vgpr_workitem_id 0
		.amdhsa_next_free_vgpr 252
		.amdhsa_next_free_sgpr 100
		.amdhsa_accum_offset 252
		.amdhsa_reserve_vcc 1
		.amdhsa_float_round_mode_32 0
		.amdhsa_float_round_mode_16_64 0
		.amdhsa_float_denorm_mode_32 3
		.amdhsa_float_denorm_mode_16_64 3
		.amdhsa_dx10_clamp 1
		.amdhsa_ieee_mode 1
		.amdhsa_fp16_overflow 0
		.amdhsa_tg_split 0
		.amdhsa_exception_fp_ieee_invalid_op 0
		.amdhsa_exception_fp_denorm_src 0
		.amdhsa_exception_fp_ieee_div_zero 0
		.amdhsa_exception_fp_ieee_overflow 0
		.amdhsa_exception_fp_ieee_underflow 0
		.amdhsa_exception_fp_ieee_inexact 0
		.amdhsa_exception_int_div_zero 0
	.end_amdhsa_kernel

amdhsa.kernels:
  - .agpr_count:     0
    .args:
      - .offset:         0
        .size:           160
        .value_kind:     by_value
      - .offset:         160
        .size:           4
        .value_kind:     hidden_block_count_x
      - .offset:         164
        .size:           4
        .value_kind:     hidden_block_count_y
      - .offset:         168
        .size:           4
        .value_kind:     hidden_block_count_z
      - .offset:         172
        .size:           2
        .value_kind:     hidden_group_size_x
      - .offset:         174
        .size:           2
        .value_kind:     hidden_group_size_y
      - .offset:         176
        .size:           2
        .value_kind:     hidden_group_size_z
      - .offset:         178
        .size:           2
        .value_kind:     hidden_remainder_x
      - .offset:         180
        .size:           2
        .value_kind:     hidden_remainder_y
      - .offset:         182
        .size:           2
        .value_kind:     hidden_remainder_z
      - .offset:         200
        .size:           8
        .value_kind:     hidden_global_offset_x
      - .offset:         208
        .size:           8
        .value_kind:     hidden_global_offset_y
      - .offset:         216
        .size:           8
        .value_kind:     hidden_global_offset_z
      - .offset:         224
        .size:           2
        .value_kind:     hidden_grid_dims
      - .offset:         280
        .size:           4
        .value_kind:     hidden_dynamic_lds_size
    .group_segment_fixed_size: 0
    .kernarg_segment_align: 8
    .kernarg_segment_size: 416
    .language:       OpenCL C
    .language_version:
      - 2
      - 0
    .max_flat_workgroup_size: 512
    .name:           _Z6mk_fwd4Args
    .private_segment_fixed_size: 0
    .sgpr_count:     106
    .sgpr_spill_count: 94
    .symbol:         _Z6mk_fwd4Args.kd
    .uniform_work_group_size: 1
    .uses_dynamic_stack: false
    .vgpr_count:     252
    .vgpr_spill_count: 0
    .wavefront_size: 64
